# conversion split plus GEMM K-loop back-edge updates moved before the closing barrier (loop-edge rotation)
# baseline (speedup 1.0000x reference)
.LBB0_326:
	ds_read_b128 v[138:141], v196
	ds_read_b128 v[142:145], v196 offset:1024
	ds_read_b128 v[146:149], v196 offset:2048
	ds_read_b128 v[150:153], v196 offset:3072
	ds_read_b128 v[182:185], v197
	ds_read_b128 v[186:189], v197 offset:1024
	ds_read_b128 v[202:205], v197 offset:2048
	ds_read_b128 v[206:209], v197 offset:3072
	s_add_u32 s0, s8, 0xfff80080
	s_addc_u32 s1, s9, -1
	s_cmp_eq_u32 s51, 28
	s_cselect_b32 s49, s2, s1
	s_cselect_b32 s48, s11, s0
	s_cselect_b32 s1, s13, s50
	s_cselect_b32 s0, s41, s43
	v_lshl_add_u64 v[4:5], s[8:9], 0, v[174:175]
	s_add_i32 m0, s34, 0xc000
	ds_read_b128 v[210:213], v198
	ds_read_b128 v[214:217], v198 offset:1024
	ds_read_b128 v[218:221], v198 offset:2048
	ds_read_b128 v[222:225], v198 offset:3072
	ds_read_b128 v[226:229], v198 offset:4096
	ds_read_b128 v[230:233], v198 offset:5120
	ds_read_b128 v[234:237], v198 offset:6144
	ds_read_b128 v[238:241], v198 offset:7168
	global_load_lds_dwordx4 v[4:5], off
	v_lshl_add_u64 v[4:5], s[8:9], 0, v[176:177]
	s_add_i32 m0, s34, 0xe000
	s_nop 0
	global_load_lds_dwordx4 v[4:5], off
	s_waitcnt vmcnt(8)
	s_waitcnt lgkmcnt(0)
	s_barrier
	s_setprio 1
	s_waitcnt lgkmcnt(0)
	v_mfma_f32_16x16x32_bf16 v[130:133], v[138:141], v[210:213], v[130:133]
	v_mfma_f32_16x16x32_bf16 v[134:137], v[146:149], v[210:213], v[134:137]
	v_mfma_f32_16x16x32_bf16 v[114:117], v[138:141], v[218:221], v[114:117]
	v_mfma_f32_16x16x32_bf16 v[118:121], v[146:149], v[218:221], v[118:121]
	v_mfma_f32_16x16x32_bf16 v[98:101], v[138:141], v[226:229], v[98:101]
	v_mfma_f32_16x16x32_bf16 v[102:105], v[146:149], v[226:229], v[102:105]
	v_mfma_f32_16x16x32_bf16 v[82:85], v[138:141], v[234:237], v[82:85]
	v_mfma_f32_16x16x32_bf16 v[86:89], v[146:149], v[234:237], v[86:89]
	v_mfma_f32_16x16x32_bf16 v[130:133], v[142:145], v[214:217], v[130:133]
	v_mfma_f32_16x16x32_bf16 v[134:137], v[150:153], v[214:217], v[134:137]
	v_mfma_f32_16x16x32_bf16 v[114:117], v[142:145], v[222:225], v[114:117]
	v_mfma_f32_16x16x32_bf16 v[118:121], v[150:153], v[222:225], v[118:121]
	v_mfma_f32_16x16x32_bf16 v[98:101], v[142:145], v[230:233], v[98:101]
	v_mfma_f32_16x16x32_bf16 v[102:105], v[150:153], v[230:233], v[102:105]
	v_mfma_f32_16x16x32_bf16 v[82:85], v[142:145], v[238:241], v[82:85]
	v_mfma_f32_16x16x32_bf16 v[86:89], v[150:153], v[238:241], v[86:89]
	s_setprio 0
	s_setprio 1
	v_mfma_f32_16x16x32_bf16 v[122:125], v[182:185], v[210:213], v[122:125]
	v_mfma_f32_16x16x32_bf16 v[126:129], v[202:205], v[210:213], v[126:129]
	v_mfma_f32_16x16x32_bf16 v[106:109], v[182:185], v[218:221], v[106:109]
	v_mfma_f32_16x16x32_bf16 v[110:113], v[202:205], v[218:221], v[110:113]
	v_mfma_f32_16x16x32_bf16 v[90:93], v[182:185], v[226:229], v[90:93]
	v_mfma_f32_16x16x32_bf16 v[94:97], v[202:205], v[226:229], v[94:97]
	v_mfma_f32_16x16x32_bf16 v[74:77], v[182:185], v[234:237], v[74:77]
	v_mfma_f32_16x16x32_bf16 v[78:81], v[202:205], v[234:237], v[78:81]
	v_mfma_f32_16x16x32_bf16 v[122:125], v[186:189], v[214:217], v[122:125]
	v_mfma_f32_16x16x32_bf16 v[126:129], v[206:209], v[214:217], v[126:129]
	v_mfma_f32_16x16x32_bf16 v[106:109], v[186:189], v[222:225], v[106:109]
	v_mfma_f32_16x16x32_bf16 v[110:113], v[206:209], v[222:225], v[110:113]
	v_mfma_f32_16x16x32_bf16 v[90:93], v[186:189], v[230:233], v[90:93]
	v_mfma_f32_16x16x32_bf16 v[94:97], v[206:209], v[230:233], v[94:97]
	v_mfma_f32_16x16x32_bf16 v[74:77], v[186:189], v[238:241], v[74:77]
	v_mfma_f32_16x16x32_bf16 v[78:81], v[206:209], v[238:241], v[78:81]
	s_setprio 0
	s_barrier
	s_add_i32 s71, s59, s21
	v_lshl_add_u64 v[4:5], s[0:1], 0, v[156:157]
	s_mov_b32 m0, s71
	ds_read_b128 v[210:213], v198 offset:16384
	ds_read_b128 v[214:217], v198 offset:17408
	ds_read_b128 v[218:221], v198 offset:18432
	ds_read_b128 v[222:225], v198 offset:19456
	ds_read_b128 v[226:229], v198 offset:20480
	ds_read_b128 v[230:233], v198 offset:21504
	ds_read_b128 v[234:237], v198 offset:22528
	ds_read_b128 v[238:241], v198 offset:23552
	global_load_lds_dwordx4 v[4:5], off
	s_add_i32 m0, s71, 0x2000
	s_add_u32 s72, s0, 0x80000
	v_lshl_add_u64 v[242:243], s[0:1], 0, v[160:161]
	s_addc_u32 s73, s1, 0
	s_add_i32 s71, s60, s21
	global_load_lds_dwordx4 v[242:243], off
	v_lshl_add_u64 v[8:9], s[72:73], 0, v[156:157]
	s_mov_b32 m0, s71
	v_lshl_add_u64 v[244:245], s[48:49], 0, v[154:155]
	global_load_lds_dwordx4 v[8:9], off
	v_lshl_add_u64 v[8:9], s[72:73], 0, v[160:161]
	s_add_i32 m0, s71, 0x2000
	v_lshl_add_u64 v[246:247], s[48:49], 0, v[158:159]
	global_load_lds_dwordx4 v[8:9], off
	s_mov_b32 m0, s34
	s_nop 0
	global_load_lds_dwordx4 v[244:245], off
	s_mov_b32 m0, s35
	s_nop 0
	global_load_lds_dwordx4 v[246:247], off
	s_waitcnt vmcnt(8)
	s_waitcnt lgkmcnt(0)
	s_barrier
	s_setprio 1
	s_waitcnt lgkmcnt(0)
	v_mfma_f32_16x16x32_bf16 v[66:69], v[138:141], v[210:213], v[66:69]
	v_mfma_f32_16x16x32_bf16 v[70:73], v[146:149], v[210:213], v[70:73]
	v_mfma_f32_16x16x32_bf16 v[50:53], v[138:141], v[218:221], v[50:53]
	v_mfma_f32_16x16x32_bf16 v[54:57], v[146:149], v[218:221], v[54:57]
	v_mfma_f32_16x16x32_bf16 v[34:37], v[138:141], v[226:229], v[34:37]
	v_mfma_f32_16x16x32_bf16 v[38:41], v[146:149], v[226:229], v[38:41]
	v_mfma_f32_16x16x32_bf16 v[18:21], v[138:141], v[234:237], v[18:21]
	v_mfma_f32_16x16x32_bf16 v[22:25], v[146:149], v[234:237], v[22:25]
	v_mfma_f32_16x16x32_bf16 v[66:69], v[142:145], v[214:217], v[66:69]
	v_mfma_f32_16x16x32_bf16 v[70:73], v[150:153], v[214:217], v[70:73]
	v_mfma_f32_16x16x32_bf16 v[50:53], v[142:145], v[222:225], v[50:53]
	v_mfma_f32_16x16x32_bf16 v[54:57], v[150:153], v[222:225], v[54:57]
	v_mfma_f32_16x16x32_bf16 v[34:37], v[142:145], v[230:233], v[34:37]
	v_mfma_f32_16x16x32_bf16 v[38:41], v[150:153], v[230:233], v[38:41]
	v_mfma_f32_16x16x32_bf16 v[18:21], v[142:145], v[238:241], v[18:21]
	v_mfma_f32_16x16x32_bf16 v[22:25], v[150:153], v[238:241], v[22:25]
	s_setprio 0
	s_setprio 1
	v_mfma_f32_16x16x32_bf16 v[58:61], v[182:185], v[210:213], v[58:61]
	v_mfma_f32_16x16x32_bf16 v[62:65], v[202:205], v[210:213], v[62:65]
	v_mfma_f32_16x16x32_bf16 v[42:45], v[182:185], v[218:221], v[42:45]
	v_mfma_f32_16x16x32_bf16 v[46:49], v[202:205], v[218:221], v[46:49]
	v_mfma_f32_16x16x32_bf16 v[26:29], v[182:185], v[226:229], v[26:29]
	v_mfma_f32_16x16x32_bf16 v[30:33], v[202:205], v[226:229], v[30:33]
	v_mfma_f32_16x16x32_bf16 v[14:17], v[182:185], v[234:237], v[14:17]
	v_mfma_f32_16x16x32_bf16 v[8:11], v[202:205], v[234:237], v[10:13]
	v_mfma_f32_16x16x32_bf16 v[58:61], v[186:189], v[214:217], v[58:61]
	v_mfma_f32_16x16x32_bf16 v[62:65], v[206:209], v[214:217], v[62:65]
	v_mfma_f32_16x16x32_bf16 v[42:45], v[186:189], v[222:225], v[42:45]
	v_mfma_f32_16x16x32_bf16 v[46:49], v[206:209], v[222:225], v[46:49]
	v_mfma_f32_16x16x32_bf16 v[26:29], v[186:189], v[230:233], v[26:29]
	v_mfma_f32_16x16x32_bf16 v[30:33], v[206:209], v[230:233], v[30:33]
	v_mfma_f32_16x16x32_bf16 v[14:17], v[186:189], v[238:241], v[14:17]
	v_mfma_f32_16x16x32_bf16 v[8:11], v[206:209], v[238:241], v[8:11]
	s_setprio 0
	s_barrier
	s_add_i32 s71, 0, 0x18000
	v_add_u32_e32 v2, s71, v192
	s_add_i32 s72, 0, 0x1c000
	ds_read_b128 v[138:141], v2
	ds_read_b128 v[142:145], v2 offset:1024
	ds_read_b128 v[146:149], v2 offset:2048
	ds_read_b128 v[150:153], v2 offset:3072
	v_add_u32_e32 v2, s72, v192
	ds_read_b128 v[182:185], v2
	ds_read_b128 v[186:189], v2 offset:1024
	ds_read_b128 v[202:205], v2 offset:2048
	ds_read_b128 v[206:209], v2 offset:3072
	s_add_u32 s48, s48, 0x80000
	s_addc_u32 s49, s49, 0
	s_mov_b32 m0, s52
	v_lshl_add_u64 v[12:13], s[48:49], 0, v[154:155]
	ds_read_b128 v[210:213], v198 offset:32768
	ds_read_b128 v[214:217], v198 offset:33792
	ds_read_b128 v[218:221], v198 offset:34816
	ds_read_b128 v[222:225], v198 offset:35840
	ds_read_b128 v[226:229], v198 offset:36864
	ds_read_b128 v[230:233], v198 offset:37888
	ds_read_b128 v[234:237], v198 offset:38912
	ds_read_b128 v[238:241], v198 offset:39936
	global_load_lds_dwordx4 v[12:13], off
	v_lshl_add_u64 v[12:13], s[48:49], 0, v[158:159]
	s_mov_b32 m0, s53
	s_nop 0
	global_load_lds_dwordx4 v[12:13], off
	s_waitcnt vmcnt(8)
	s_waitcnt lgkmcnt(0)
	s_barrier
	s_setprio 1
	s_waitcnt lgkmcnt(0)
	v_mfma_f32_16x16x32_bf16 v[130:133], v[138:141], v[210:213], v[130:133]
	v_mfma_f32_16x16x32_bf16 v[134:137], v[146:149], v[210:213], v[134:137]
	v_mfma_f32_16x16x32_bf16 v[114:117], v[138:141], v[218:221], v[114:117]
	v_mfma_f32_16x16x32_bf16 v[118:121], v[146:149], v[218:221], v[118:121]
	v_mfma_f32_16x16x32_bf16 v[98:101], v[138:141], v[226:229], v[98:101]
	v_mfma_f32_16x16x32_bf16 v[102:105], v[146:149], v[226:229], v[102:105]
	v_mfma_f32_16x16x32_bf16 v[82:85], v[138:141], v[234:237], v[82:85]
	v_mfma_f32_16x16x32_bf16 v[86:89], v[146:149], v[234:237], v[86:89]
	v_mfma_f32_16x16x32_bf16 v[130:133], v[142:145], v[214:217], v[130:133]
	v_mfma_f32_16x16x32_bf16 v[134:137], v[150:153], v[214:217], v[134:137]
	v_mfma_f32_16x16x32_bf16 v[114:117], v[142:145], v[222:225], v[114:117]
	v_mfma_f32_16x16x32_bf16 v[118:121], v[150:153], v[222:225], v[118:121]
	v_mfma_f32_16x16x32_bf16 v[98:101], v[142:145], v[230:233], v[98:101]
	v_mfma_f32_16x16x32_bf16 v[102:105], v[150:153], v[230:233], v[102:105]
	v_mfma_f32_16x16x32_bf16 v[82:85], v[142:145], v[238:241], v[82:85]
	v_mfma_f32_16x16x32_bf16 v[86:89], v[150:153], v[238:241], v[86:89]
	s_setprio 0
	s_setprio 1
	v_mfma_f32_16x16x32_bf16 v[122:125], v[182:185], v[210:213], v[122:125]
	v_mfma_f32_16x16x32_bf16 v[126:129], v[202:205], v[210:213], v[126:129]
	v_mfma_f32_16x16x32_bf16 v[106:109], v[182:185], v[218:221], v[106:109]
	v_mfma_f32_16x16x32_bf16 v[110:113], v[202:205], v[218:221], v[110:113]
	v_mfma_f32_16x16x32_bf16 v[90:93], v[182:185], v[226:229], v[90:93]
	v_mfma_f32_16x16x32_bf16 v[94:97], v[202:205], v[226:229], v[94:97]
	v_mfma_f32_16x16x32_bf16 v[74:77], v[182:185], v[234:237], v[74:77]
	v_mfma_f32_16x16x32_bf16 v[78:81], v[202:205], v[234:237], v[78:81]
	v_mfma_f32_16x16x32_bf16 v[122:125], v[186:189], v[214:217], v[122:125]
	v_mfma_f32_16x16x32_bf16 v[126:129], v[206:209], v[214:217], v[126:129]
	v_mfma_f32_16x16x32_bf16 v[106:109], v[186:189], v[222:225], v[106:109]
	v_mfma_f32_16x16x32_bf16 v[110:113], v[206:209], v[222:225], v[110:113]
	v_mfma_f32_16x16x32_bf16 v[90:93], v[186:189], v[230:233], v[90:93]
	v_mfma_f32_16x16x32_bf16 v[94:97], v[206:209], v[230:233], v[94:97]
	v_mfma_f32_16x16x32_bf16 v[74:77], v[186:189], v[238:241], v[74:77]
	v_mfma_f32_16x16x32_bf16 v[78:81], v[206:209], v[238:241], v[78:81]
	s_setprio 0
	s_barrier
	s_add_i32 s48, s71, s21
	v_lshl_add_u64 v[4:5], v[4:5], 0, s[36:37]
	s_mov_b32 m0, s48
	ds_read_b128 v[210:213], v198 offset:49152
	ds_read_b128 v[214:217], v198 offset:50176
	ds_read_b128 v[218:221], v198 offset:51200
	ds_read_b128 v[222:225], v198 offset:52224
	ds_read_b128 v[226:229], v198 offset:53248
	ds_read_b128 v[230:233], v198 offset:54272
	ds_read_b128 v[234:237], v198 offset:55296
	ds_read_b128 v[238:241], v198 offset:56320
	global_load_lds_dwordx4 v[4:5], off
	s_add_i32 m0, s48, 0x2000
	s_add_u32 s0, s0, 0x80080
	v_lshl_add_u64 v[4:5], v[242:243], 0, s[36:37]
	s_addc_u32 s1, s1, 0
	s_add_i32 s48, s72, s21
	global_load_lds_dwordx4 v[4:5], off
	v_lshl_add_u64 v[4:5], s[0:1], 0, v[156:157]
	s_mov_b32 m0, s48
	s_nop 0
	global_load_lds_dwordx4 v[4:5], off
	v_lshl_add_u64 v[4:5], s[0:1], 0, v[160:161]
	s_add_i32 m0, s48, 0x2000
	s_nop 0
	global_load_lds_dwordx4 v[4:5], off
	v_lshl_add_u64 v[4:5], v[244:245], 0, s[36:37]
	s_mov_b32 m0, s56
	s_nop 0
	global_load_lds_dwordx4 v[4:5], off
	v_lshl_add_u64 v[4:5], v[246:247], 0, s[36:37]
	s_mov_b32 m0, s57
	s_nop 0
	global_load_lds_dwordx4 v[4:5], off
	s_waitcnt vmcnt(8)
	s_waitcnt lgkmcnt(0)
	s_barrier
	s_setprio 1
	s_waitcnt lgkmcnt(0)
	v_mfma_f32_16x16x32_bf16 v[66:69], v[138:141], v[210:213], v[66:69]
	v_mfma_f32_16x16x32_bf16 v[70:73], v[146:149], v[210:213], v[70:73]
	v_mfma_f32_16x16x32_bf16 v[50:53], v[138:141], v[218:221], v[50:53]
	v_mfma_f32_16x16x32_bf16 v[54:57], v[146:149], v[218:221], v[54:57]
	v_mfma_f32_16x16x32_bf16 v[34:37], v[138:141], v[226:229], v[34:37]
	v_mfma_f32_16x16x32_bf16 v[38:41], v[146:149], v[226:229], v[38:41]
	v_mfma_f32_16x16x32_bf16 v[18:21], v[138:141], v[234:237], v[18:21]
	v_mfma_f32_16x16x32_bf16 v[22:25], v[146:149], v[234:237], v[22:25]
	v_mfma_f32_16x16x32_bf16 v[66:69], v[142:145], v[214:217], v[66:69]
	v_mfma_f32_16x16x32_bf16 v[70:73], v[150:153], v[214:217], v[70:73]
	v_mfma_f32_16x16x32_bf16 v[50:53], v[142:145], v[222:225], v[50:53]
	v_mfma_f32_16x16x32_bf16 v[54:57], v[150:153], v[222:225], v[54:57]
	v_mfma_f32_16x16x32_bf16 v[34:37], v[142:145], v[230:233], v[34:37]
	v_mfma_f32_16x16x32_bf16 v[38:41], v[150:153], v[230:233], v[38:41]
	v_mfma_f32_16x16x32_bf16 v[18:21], v[142:145], v[238:241], v[18:21]
	v_mfma_f32_16x16x32_bf16 v[22:25], v[150:153], v[238:241], v[22:25]
	s_setprio 0
	s_setprio 1
	v_mfma_f32_16x16x32_bf16 v[58:61], v[182:185], v[210:213], v[58:61]
	v_mfma_f32_16x16x32_bf16 v[62:65], v[202:205], v[210:213], v[62:65]
	v_mfma_f32_16x16x32_bf16 v[42:45], v[182:185], v[218:221], v[42:45]
	v_mfma_f32_16x16x32_bf16 v[46:49], v[202:205], v[218:221], v[46:49]
	v_mfma_f32_16x16x32_bf16 v[26:29], v[182:185], v[226:229], v[26:29]
	v_mfma_f32_16x16x32_bf16 v[30:33], v[202:205], v[226:229], v[30:33]
	v_mfma_f32_16x16x32_bf16 v[12:15], v[182:185], v[234:237], v[14:17]
	v_mfma_f32_16x16x32_bf16 v[8:11], v[202:205], v[234:237], v[8:11]
	v_mfma_f32_16x16x32_bf16 v[58:61], v[186:189], v[214:217], v[58:61]
	v_mfma_f32_16x16x32_bf16 v[62:65], v[206:209], v[214:217], v[62:65]
	v_mfma_f32_16x16x32_bf16 v[42:45], v[186:189], v[222:225], v[42:45]
	v_mfma_f32_16x16x32_bf16 v[46:49], v[206:209], v[222:225], v[46:49]
	v_mfma_f32_16x16x32_bf16 v[26:29], v[186:189], v[230:233], v[26:29]
	v_mfma_f32_16x16x32_bf16 v[30:33], v[206:209], v[230:233], v[30:33]
	v_mfma_f32_16x16x32_bf16 v[14:17], v[186:189], v[238:241], v[12:15]
	v_mfma_f32_16x16x32_bf16 v[10:13], v[206:209], v[238:241], v[8:11]
	s_setprio 0
	s_add_i32 s51, s51, 2
	s_add_u32 s8, s8, 0x100
	s_addc_u32 s9, s9, 0
	s_add_u32 s43, s43, 0x100
	s_addc_u32 s50, s50, 0
	s_cmp_gt_u32 s51, 29
	s_barrier
	s_cbranch_scc0 .LBB0_326
	s_and_b64 vcc, exec, s[38:39]
	s_cbranch_vccz .LBB0_329
	s_barrier

.LBB0_722:
	ds_read_b128 v[156:159], v149
	ds_read_b128 v[160:163], v149 offset:1024
	ds_read_b128 v[164:167], v149 offset:2048
	ds_read_b128 v[168:171], v149 offset:3072
	ds_read_b128 v[172:175], v150
	ds_read_b128 v[176:179], v150 offset:1024
	ds_read_b128 v[180:183], v150 offset:2048
	ds_read_b128 v[184:187], v150 offset:3072
	s_add_u32 s0, s28, 0xfffe8080
	s_addc_u32 s1, s29, -1
	s_cmp_eq_u32 s56, 2
	s_cselect_b32 s31, s19, s1
	s_cselect_b32 s30, s18, s0
	s_cselect_b32 s1, s23, s13
	s_cselect_b32 s0, s22, s2
	s_mov_b32 m0, s44
	v_lshl_add_u64 v[188:189], s[28:29], 0, v[140:141]
	ds_read_b128 v[192:195], v151
	ds_read_b128 v[196:199], v151 offset:1024
	ds_read_b128 v[200:203], v151 offset:2048
	ds_read_b128 v[204:207], v151 offset:3072
	ds_read_b128 v[208:211], v151 offset:4096
	ds_read_b128 v[212:215], v151 offset:5120
	ds_read_b128 v[216:219], v151 offset:6144
	ds_read_b128 v[220:223], v151 offset:7168
	global_load_lds_dwordx4 v[188:189], off
	v_lshl_add_u64 v[188:189], s[28:29], 0, v[142:143]
	s_mov_b32 m0, s45
	s_nop 0
	global_load_lds_dwordx4 v[188:189], off
	s_waitcnt vmcnt(8)
	s_waitcnt lgkmcnt(0)
	s_barrier
	s_setprio 1
	s_waitcnt lgkmcnt(0)
	v_mfma_f32_16x16x32_bf16 v[126:129], v[156:159], v[192:195], v[126:129]
	v_mfma_f32_16x16x32_bf16 v[122:125], v[164:167], v[192:195], v[122:125]
	v_mfma_f32_16x16x32_bf16 v[110:113], v[156:159], v[200:203], v[110:113]
	v_mfma_f32_16x16x32_bf16 v[106:109], v[164:167], v[200:203], v[106:109]
	v_mfma_f32_16x16x32_bf16 v[94:97], v[156:159], v[208:211], v[94:97]
	v_mfma_f32_16x16x32_bf16 v[90:93], v[164:167], v[208:211], v[90:93]
	v_mfma_f32_16x16x32_bf16 v[78:81], v[156:159], v[216:219], v[78:81]
	v_mfma_f32_16x16x32_bf16 v[74:77], v[164:167], v[216:219], v[74:77]
	v_mfma_f32_16x16x32_bf16 v[126:129], v[160:163], v[196:199], v[126:129]
	v_mfma_f32_16x16x32_bf16 v[122:125], v[168:171], v[196:199], v[122:125]
	v_mfma_f32_16x16x32_bf16 v[110:113], v[160:163], v[204:207], v[110:113]
	v_mfma_f32_16x16x32_bf16 v[106:109], v[168:171], v[204:207], v[106:109]
	v_mfma_f32_16x16x32_bf16 v[94:97], v[160:163], v[212:215], v[94:97]
	v_mfma_f32_16x16x32_bf16 v[90:93], v[168:171], v[212:215], v[90:93]
	v_mfma_f32_16x16x32_bf16 v[78:81], v[160:163], v[220:223], v[78:81]
	v_mfma_f32_16x16x32_bf16 v[74:77], v[168:171], v[220:223], v[74:77]
	s_setprio 0
	s_setprio 1
	v_mfma_f32_16x16x32_bf16 v[118:121], v[172:175], v[192:195], v[118:121]
	v_mfma_f32_16x16x32_bf16 v[114:117], v[180:183], v[192:195], v[114:117]
	v_mfma_f32_16x16x32_bf16 v[102:105], v[172:175], v[200:203], v[102:105]
	v_mfma_f32_16x16x32_bf16 v[98:101], v[180:183], v[200:203], v[98:101]
	v_mfma_f32_16x16x32_bf16 v[86:89], v[172:175], v[208:211], v[86:89]
	v_mfma_f32_16x16x32_bf16 v[82:85], v[180:183], v[208:211], v[82:85]
	v_mfma_f32_16x16x32_bf16 v[70:73], v[172:175], v[216:219], v[70:73]
	v_mfma_f32_16x16x32_bf16 v[66:69], v[180:183], v[216:219], v[66:69]
	v_mfma_f32_16x16x32_bf16 v[118:121], v[176:179], v[196:199], v[118:121]
	v_mfma_f32_16x16x32_bf16 v[114:117], v[184:187], v[196:199], v[114:117]
	v_mfma_f32_16x16x32_bf16 v[102:105], v[176:179], v[204:207], v[102:105]
	v_mfma_f32_16x16x32_bf16 v[98:101], v[184:187], v[204:207], v[98:101]
	v_mfma_f32_16x16x32_bf16 v[86:89], v[176:179], v[212:215], v[86:89]
	v_mfma_f32_16x16x32_bf16 v[82:85], v[184:187], v[212:215], v[82:85]
	v_mfma_f32_16x16x32_bf16 v[70:73], v[176:179], v[220:223], v[70:73]
	v_mfma_f32_16x16x32_bf16 v[66:69], v[184:187], v[220:223], v[66:69]
	s_setprio 0
	s_barrier
	s_mov_b32 m0, s46
	v_lshl_add_u64 v[188:189], s[0:1], 0, v[134:135]
	s_add_u32 s58, s0, 0x18000
	ds_read_b128 v[192:195], v151 offset:16384
	ds_read_b128 v[196:199], v151 offset:17408
	ds_read_b128 v[200:203], v151 offset:18432
	ds_read_b128 v[204:207], v151 offset:19456
	ds_read_b128 v[208:211], v151 offset:20480
	ds_read_b128 v[212:215], v151 offset:21504
	ds_read_b128 v[216:219], v151 offset:22528
	ds_read_b128 v[220:223], v151 offset:23552
	global_load_lds_dwordx4 v[188:189], off
	v_lshl_add_u64 v[224:225], s[0:1], 0, v[130:131]
	s_mov_b32 m0, s47
	s_addc_u32 s59, s1, 0
	global_load_lds_dwordx4 v[224:225], off
	v_lshl_add_u64 v[226:227], s[58:59], 0, v[134:135]
	s_mov_b32 m0, s48
	v_lshl_add_u64 v[228:229], s[30:31], 0, v[132:133]
	global_load_lds_dwordx4 v[226:227], off
	v_lshl_add_u64 v[226:227], s[58:59], 0, v[130:131]
	s_mov_b32 m0, s49
	s_nop 0
	global_load_lds_dwordx4 v[226:227], off
	v_lshl_add_u64 v[226:227], s[30:31], 0, v[136:137]
	s_mov_b32 m0, s27
	s_nop 0
	global_load_lds_dwordx4 v[226:227], off
	s_mov_b32 m0, s20
	s_nop 0
	global_load_lds_dwordx4 v[228:229], off
	s_waitcnt vmcnt(8)
	s_waitcnt lgkmcnt(0)
	s_barrier
	s_setprio 1
	s_waitcnt lgkmcnt(0)
	v_mfma_f32_16x16x32_bf16 v[62:65], v[156:159], v[192:195], v[62:65]
	v_mfma_f32_16x16x32_bf16 v[58:61], v[164:167], v[192:195], v[58:61]
	v_mfma_f32_16x16x32_bf16 v[46:49], v[156:159], v[200:203], v[46:49]
	v_mfma_f32_16x16x32_bf16 v[42:45], v[164:167], v[200:203], v[42:45]
	v_mfma_f32_16x16x32_bf16 v[30:33], v[156:159], v[208:211], v[30:33]
	v_mfma_f32_16x16x32_bf16 v[26:29], v[164:167], v[208:211], v[26:29]
	v_mfma_f32_16x16x32_bf16 v[14:17], v[156:159], v[216:219], v[14:17]
	v_mfma_f32_16x16x32_bf16 v[10:13], v[164:167], v[216:219], v[10:13]
	v_mfma_f32_16x16x32_bf16 v[62:65], v[160:163], v[196:199], v[62:65]
	v_mfma_f32_16x16x32_bf16 v[58:61], v[168:171], v[196:199], v[58:61]
	v_mfma_f32_16x16x32_bf16 v[46:49], v[160:163], v[204:207], v[46:49]
	v_mfma_f32_16x16x32_bf16 v[42:45], v[168:171], v[204:207], v[42:45]
	v_mfma_f32_16x16x32_bf16 v[30:33], v[160:163], v[212:215], v[30:33]
	v_mfma_f32_16x16x32_bf16 v[26:29], v[168:171], v[212:215], v[26:29]
	v_mfma_f32_16x16x32_bf16 v[14:17], v[160:163], v[220:223], v[14:17]
	v_mfma_f32_16x16x32_bf16 v[10:13], v[168:171], v[220:223], v[10:13]
	s_setprio 0
	s_setprio 1
	v_mfma_f32_16x16x32_bf16 v[54:57], v[172:175], v[192:195], v[54:57]
	v_mfma_f32_16x16x32_bf16 v[50:53], v[180:183], v[192:195], v[50:53]
	v_mfma_f32_16x16x32_bf16 v[38:41], v[172:175], v[200:203], v[38:41]
	v_mfma_f32_16x16x32_bf16 v[34:37], v[180:183], v[200:203], v[34:37]
	v_mfma_f32_16x16x32_bf16 v[22:25], v[172:175], v[208:211], v[22:25]
	v_mfma_f32_16x16x32_bf16 v[18:21], v[180:183], v[208:211], v[18:21]
	v_mfma_f32_16x16x32_bf16 v[6:9], v[172:175], v[216:219], v[6:9]
	v_mfma_f32_16x16x32_bf16 v[2:5], v[180:183], v[216:219], v[2:5]
	v_mfma_f32_16x16x32_bf16 v[54:57], v[176:179], v[196:199], v[54:57]
	v_mfma_f32_16x16x32_bf16 v[50:53], v[184:187], v[196:199], v[50:53]
	v_mfma_f32_16x16x32_bf16 v[38:41], v[176:179], v[204:207], v[38:41]
	v_mfma_f32_16x16x32_bf16 v[34:37], v[184:187], v[204:207], v[34:37]
	v_mfma_f32_16x16x32_bf16 v[22:25], v[176:179], v[212:215], v[22:25]
	v_mfma_f32_16x16x32_bf16 v[18:21], v[184:187], v[212:215], v[18:21]
	v_mfma_f32_16x16x32_bf16 v[6:9], v[176:179], v[220:223], v[6:9]
	v_mfma_f32_16x16x32_bf16 v[2:5], v[184:187], v[220:223], v[2:5]
	s_setprio 0
	s_barrier
	ds_read_b128 v[156:159], v152
	ds_read_b128 v[160:163], v152 offset:1024
	ds_read_b128 v[164:167], v152 offset:2048
	ds_read_b128 v[168:171], v152 offset:3072
	ds_read_b128 v[172:175], v153
	ds_read_b128 v[176:179], v153 offset:1024
	ds_read_b128 v[180:183], v153 offset:2048
	ds_read_b128 v[184:187], v153 offset:3072
	s_add_u32 s30, s30, 0x18000
	s_addc_u32 s31, s31, 0
	s_mov_b32 m0, s21
	v_lshl_add_u64 v[230:231], s[30:31], 0, v[136:137]
	ds_read_b128 v[192:195], v151 offset:32768
	ds_read_b128 v[196:199], v151 offset:33792
	ds_read_b128 v[200:203], v151 offset:34816
	ds_read_b128 v[204:207], v151 offset:35840
	ds_read_b128 v[208:211], v151 offset:36864
	ds_read_b128 v[212:215], v151 offset:37888
	ds_read_b128 v[216:219], v151 offset:38912
	ds_read_b128 v[220:223], v151 offset:39936
	global_load_lds_dwordx4 v[230:231], off
	v_lshl_add_u64 v[230:231], s[30:31], 0, v[132:133]
	s_mov_b32 m0, s34
	s_nop 0
	global_load_lds_dwordx4 v[230:231], off
	s_waitcnt vmcnt(8)
	s_waitcnt lgkmcnt(0)
	s_barrier
	s_setprio 1
	s_waitcnt lgkmcnt(0)
	v_mfma_f32_16x16x32_bf16 v[126:129], v[156:159], v[192:195], v[126:129]
	v_mfma_f32_16x16x32_bf16 v[122:125], v[164:167], v[192:195], v[122:125]
	v_mfma_f32_16x16x32_bf16 v[110:113], v[156:159], v[200:203], v[110:113]
	v_mfma_f32_16x16x32_bf16 v[106:109], v[164:167], v[200:203], v[106:109]
	v_mfma_f32_16x16x32_bf16 v[94:97], v[156:159], v[208:211], v[94:97]
	v_mfma_f32_16x16x32_bf16 v[90:93], v[164:167], v[208:211], v[90:93]
	v_mfma_f32_16x16x32_bf16 v[78:81], v[156:159], v[216:219], v[78:81]
	v_mfma_f32_16x16x32_bf16 v[74:77], v[164:167], v[216:219], v[74:77]
	v_mfma_f32_16x16x32_bf16 v[126:129], v[160:163], v[196:199], v[126:129]
	v_mfma_f32_16x16x32_bf16 v[122:125], v[168:171], v[196:199], v[122:125]
	v_mfma_f32_16x16x32_bf16 v[110:113], v[160:163], v[204:207], v[110:113]
	v_mfma_f32_16x16x32_bf16 v[106:109], v[168:171], v[204:207], v[106:109]
	v_mfma_f32_16x16x32_bf16 v[94:97], v[160:163], v[212:215], v[94:97]
	v_mfma_f32_16x16x32_bf16 v[90:93], v[168:171], v[212:215], v[90:93]
	v_mfma_f32_16x16x32_bf16 v[78:81], v[160:163], v[220:223], v[78:81]
	v_mfma_f32_16x16x32_bf16 v[74:77], v[168:171], v[220:223], v[74:77]
	s_setprio 0
	s_setprio 1
	v_mfma_f32_16x16x32_bf16 v[118:121], v[172:175], v[192:195], v[118:121]
	v_mfma_f32_16x16x32_bf16 v[114:117], v[180:183], v[192:195], v[114:117]
	v_mfma_f32_16x16x32_bf16 v[102:105], v[172:175], v[200:203], v[102:105]
	v_mfma_f32_16x16x32_bf16 v[98:101], v[180:183], v[200:203], v[98:101]
	v_mfma_f32_16x16x32_bf16 v[86:89], v[172:175], v[208:211], v[86:89]
	v_mfma_f32_16x16x32_bf16 v[82:85], v[180:183], v[208:211], v[82:85]
	v_mfma_f32_16x16x32_bf16 v[70:73], v[172:175], v[216:219], v[70:73]
	v_mfma_f32_16x16x32_bf16 v[66:69], v[180:183], v[216:219], v[66:69]
	v_mfma_f32_16x16x32_bf16 v[118:121], v[176:179], v[196:199], v[118:121]
	v_mfma_f32_16x16x32_bf16 v[114:117], v[184:187], v[196:199], v[114:117]
	v_mfma_f32_16x16x32_bf16 v[102:105], v[176:179], v[204:207], v[102:105]
	v_mfma_f32_16x16x32_bf16 v[98:101], v[184:187], v[204:207], v[98:101]
	v_mfma_f32_16x16x32_bf16 v[86:89], v[176:179], v[212:215], v[86:89]
	v_mfma_f32_16x16x32_bf16 v[82:85], v[184:187], v[212:215], v[82:85]
	v_mfma_f32_16x16x32_bf16 v[70:73], v[176:179], v[220:223], v[70:73]
	v_mfma_f32_16x16x32_bf16 v[66:69], v[184:187], v[220:223], v[66:69]
	s_setprio 0
	s_barrier
	s_mov_b32 m0, s50
	v_lshl_add_u64 v[188:189], v[188:189], 0, s[10:11]
	s_add_u32 s0, s0, 0x18080
	ds_read_b128 v[192:195], v151 offset:49152
	ds_read_b128 v[196:199], v151 offset:50176
	ds_read_b128 v[200:203], v151 offset:51200
	ds_read_b128 v[204:207], v151 offset:52224
	ds_read_b128 v[208:211], v151 offset:53248
	ds_read_b128 v[212:215], v151 offset:54272
	ds_read_b128 v[216:219], v151 offset:55296
	ds_read_b128 v[220:223], v151 offset:56320
	global_load_lds_dwordx4 v[188:189], off
	v_lshl_add_u64 v[188:189], v[224:225], 0, s[10:11]
	s_mov_b32 m0, s51
	s_addc_u32 s1, s1, 0
	global_load_lds_dwordx4 v[188:189], off
	v_lshl_add_u64 v[188:189], s[0:1], 0, v[134:135]
	s_mov_b32 m0, s52
	s_nop 0
	global_load_lds_dwordx4 v[188:189], off
	v_lshl_add_u64 v[188:189], s[0:1], 0, v[130:131]
	s_mov_b32 m0, s53
	s_nop 0
	global_load_lds_dwordx4 v[188:189], off
	v_lshl_add_u64 v[188:189], v[226:227], 0, s[10:11]
	s_mov_b32 m0, s36
	s_nop 0
	global_load_lds_dwordx4 v[188:189], off
	v_lshl_add_u64 v[188:189], v[228:229], 0, s[10:11]
	s_mov_b32 m0, s37
	s_nop 0
	global_load_lds_dwordx4 v[188:189], off
	s_waitcnt vmcnt(8)
	s_waitcnt lgkmcnt(0)
	s_barrier
	s_setprio 1
	s_waitcnt lgkmcnt(0)
	v_mfma_f32_16x16x32_bf16 v[62:65], v[156:159], v[192:195], v[62:65]
	v_mfma_f32_16x16x32_bf16 v[58:61], v[164:167], v[192:195], v[58:61]
	v_mfma_f32_16x16x32_bf16 v[46:49], v[156:159], v[200:203], v[46:49]
	v_mfma_f32_16x16x32_bf16 v[42:45], v[164:167], v[200:203], v[42:45]
	v_mfma_f32_16x16x32_bf16 v[30:33], v[156:159], v[208:211], v[30:33]
	v_mfma_f32_16x16x32_bf16 v[26:29], v[164:167], v[208:211], v[26:29]
	v_mfma_f32_16x16x32_bf16 v[14:17], v[156:159], v[216:219], v[14:17]
	v_mfma_f32_16x16x32_bf16 v[10:13], v[164:167], v[216:219], v[10:13]
	v_mfma_f32_16x16x32_bf16 v[62:65], v[160:163], v[196:199], v[62:65]
	v_mfma_f32_16x16x32_bf16 v[58:61], v[168:171], v[196:199], v[58:61]
	v_mfma_f32_16x16x32_bf16 v[46:49], v[160:163], v[204:207], v[46:49]
	v_mfma_f32_16x16x32_bf16 v[42:45], v[168:171], v[204:207], v[42:45]
	v_mfma_f32_16x16x32_bf16 v[30:33], v[160:163], v[212:215], v[30:33]
	v_mfma_f32_16x16x32_bf16 v[26:29], v[168:171], v[212:215], v[26:29]
	v_mfma_f32_16x16x32_bf16 v[14:17], v[160:163], v[220:223], v[14:17]
	v_mfma_f32_16x16x32_bf16 v[10:13], v[168:171], v[220:223], v[10:13]
	s_setprio 0
	s_setprio 1
	v_mfma_f32_16x16x32_bf16 v[54:57], v[172:175], v[192:195], v[54:57]
	v_mfma_f32_16x16x32_bf16 v[50:53], v[180:183], v[192:195], v[50:53]
	v_mfma_f32_16x16x32_bf16 v[38:41], v[172:175], v[200:203], v[38:41]
	v_mfma_f32_16x16x32_bf16 v[34:37], v[180:183], v[200:203], v[34:37]
	v_mfma_f32_16x16x32_bf16 v[22:25], v[172:175], v[208:211], v[22:25]
	v_mfma_f32_16x16x32_bf16 v[18:21], v[180:183], v[208:211], v[18:21]
	v_mfma_f32_16x16x32_bf16 v[6:9], v[172:175], v[216:219], v[6:9]
	v_mfma_f32_16x16x32_bf16 v[2:5], v[180:183], v[216:219], v[2:5]
	v_mfma_f32_16x16x32_bf16 v[54:57], v[176:179], v[196:199], v[54:57]
	v_mfma_f32_16x16x32_bf16 v[50:53], v[184:187], v[196:199], v[50:53]
	v_mfma_f32_16x16x32_bf16 v[38:41], v[176:179], v[204:207], v[38:41]
	v_mfma_f32_16x16x32_bf16 v[34:37], v[184:187], v[204:207], v[34:37]
	v_mfma_f32_16x16x32_bf16 v[22:25], v[176:179], v[212:215], v[22:25]
	v_mfma_f32_16x16x32_bf16 v[18:21], v[184:187], v[212:215], v[18:21]
	v_mfma_f32_16x16x32_bf16 v[6:9], v[176:179], v[220:223], v[6:9]
	v_mfma_f32_16x16x32_bf16 v[2:5], v[184:187], v[220:223], v[2:5]
	s_setprio 0
	s_add_i32 s56, s56, 2
	s_add_u32 s28, s28, 0x100
	s_addc_u32 s29, s29, 0
	s_add_u32 s2, s2, 0x100
	s_addc_u32 s13, s13, 0
	s_cmp_gt_u32 s56, 3
	s_barrier
	s_cbranch_scc0 .LBB0_722
	s_and_b64 vcc, exec, s[16:17]
	s_cbranch_vccz .LBB0_725
	s_barrier

.LBB0_892:
	ds_read_b128 v[26:29], v188
	ds_read_b128 v[30:33], v188 offset:1024
	ds_read_b128 v[18:21], v188 offset:2048
	ds_read_b128 v[22:25], v188 offset:3072
	ds_read_b128 v[10:13], v189
	ds_read_b128 v[14:17], v189 offset:1024
	ds_read_b128 v[2:5], v189 offset:2048
	ds_read_b128 v[6:9], v189 offset:3072
	s_add_u32 s0, s42, 0xfffe0080
	s_addc_u32 s1, s43, -1
	s_cmp_eq_u32 s57, 4
	s_cselect_b32 s45, s31, s1
	s_cselect_b32 s44, s53, s0
	s_cselect_b32 s1, s29, s56
	s_cselect_b32 s0, s54, s55
	v_lshl_add_u64 v[216:217], s[42:43], 0, v[170:171]
	s_add_i32 m0, s25, 0xc000
	ds_read_b128 v[178:181], v190
	ds_read_b128 v[182:185], v190 offset:1024
	ds_read_b128 v[192:195], v190 offset:2048
	ds_read_b128 v[196:199], v190 offset:3072
	ds_read_b128 v[200:203], v190 offset:4096
	ds_read_b128 v[204:207], v190 offset:5120
	ds_read_b128 v[208:211], v190 offset:6144
	ds_read_b128 v[212:215], v190 offset:7168
	global_load_lds_dwordx4 v[216:217], off
	v_lshl_add_u64 v[216:217], s[42:43], 0, v[172:173]
	s_add_i32 m0, s25, 0xe000
	s_nop 0
	global_load_lds_dwordx4 v[216:217], off
	s_waitcnt vmcnt(8)
	s_waitcnt lgkmcnt(0)
	s_barrier
	s_setprio 1
	s_waitcnt lgkmcnt(0)
	v_mfma_f32_16x16x128_f8f6f4 v[158:161], v[26:33], v[178:185], v[158:161]
	v_mfma_f32_16x16x128_f8f6f4 v[154:157], v[18:25], v[178:185], v[154:157]
	v_mfma_f32_16x16x128_f8f6f4 v[142:145], v[26:33], v[192:199], v[142:145]
	v_mfma_f32_16x16x128_f8f6f4 v[138:141], v[18:25], v[192:199], v[138:141]
	v_mfma_f32_16x16x128_f8f6f4 v[126:129], v[26:33], v[200:207], v[126:129]
	v_mfma_f32_16x16x128_f8f6f4 v[122:125], v[18:25], v[200:207], v[122:125]
	v_mfma_f32_16x16x128_f8f6f4 v[110:113], v[26:33], v[208:215], v[110:113]
	v_mfma_f32_16x16x128_f8f6f4 v[106:109], v[18:25], v[208:215], v[106:109]
	s_setprio 0
	s_setprio 1
	v_mfma_f32_16x16x128_f8f6f4 v[150:153], v[10:17], v[178:185], v[150:153]
	v_mfma_f32_16x16x128_f8f6f4 v[146:149], v[2:9], v[178:185], v[146:149]
	v_mfma_f32_16x16x128_f8f6f4 v[134:137], v[10:17], v[192:199], v[134:137]
	v_mfma_f32_16x16x128_f8f6f4 v[130:133], v[2:9], v[192:199], v[130:133]
	v_mfma_f32_16x16x128_f8f6f4 v[118:121], v[10:17], v[200:207], v[118:121]
	v_mfma_f32_16x16x128_f8f6f4 v[114:117], v[2:9], v[200:207], v[114:117]
	v_mfma_f32_16x16x128_f8f6f4 v[102:105], v[10:17], v[208:215], v[102:105]
	v_mfma_f32_16x16x128_f8f6f4 v[98:101], v[2:9], v[208:215], v[98:101]
	s_setprio 0
	s_barrier
	s_add_i32 s58, s46, s2
	v_lshl_add_u64 v[178:179], s[0:1], 0, v[166:167]
	s_mov_b32 m0, s58
	ds_read_b128 v[192:195], v190 offset:16384
	ds_read_b128 v[196:199], v190 offset:17408
	ds_read_b128 v[200:203], v190 offset:18432
	ds_read_b128 v[204:207], v190 offset:19456
	ds_read_b128 v[208:211], v190 offset:20480
	ds_read_b128 v[212:215], v190 offset:21504
	ds_read_b128 v[216:219], v190 offset:22528
	ds_read_b128 v[220:223], v190 offset:23552
	global_load_lds_dwordx4 v[178:179], off
	s_add_i32 m0, s58, 0x2000
	s_add_u32 s58, s0, 0x20000
	v_lshl_add_u64 v[180:181], s[0:1], 0, v[162:163]
	s_addc_u32 s59, s1, 0
	s_add_i32 s60, s47, s2
	global_load_lds_dwordx4 v[180:181], off
	v_lshl_add_u64 v[182:183], s[58:59], 0, v[166:167]
	s_mov_b32 m0, s60
	v_lshl_add_u64 v[184:185], s[44:45], 0, v[164:165]
	global_load_lds_dwordx4 v[182:183], off
	v_lshl_add_u64 v[182:183], s[58:59], 0, v[162:163]
	s_add_i32 m0, s60, 0x2000
	s_nop 0
	global_load_lds_dwordx4 v[182:183], off
	v_lshl_add_u64 v[182:183], s[44:45], 0, v[168:169]
	s_mov_b32 m0, s25
	s_nop 0
	global_load_lds_dwordx4 v[182:183], off
	s_mov_b32 m0, s26
	s_nop 0
	global_load_lds_dwordx4 v[184:185], off
	s_waitcnt vmcnt(8)
	s_waitcnt lgkmcnt(0)
	s_barrier
	s_setprio 1
	s_waitcnt lgkmcnt(0)
	v_mfma_f32_16x16x128_f8f6f4 v[94:97], v[26:33], v[192:199], v[94:97]
	v_mfma_f32_16x16x128_f8f6f4 v[90:93], v[18:25], v[192:199], v[90:93]
	v_mfma_f32_16x16x128_f8f6f4 v[78:81], v[26:33], v[200:207], v[78:81]
	v_mfma_f32_16x16x128_f8f6f4 v[74:77], v[18:25], v[200:207], v[74:77]
	v_mfma_f32_16x16x128_f8f6f4 v[62:65], v[26:33], v[208:215], v[62:65]
	v_mfma_f32_16x16x128_f8f6f4 v[58:61], v[18:25], v[208:215], v[58:61]
	v_mfma_f32_16x16x128_f8f6f4 v[46:49], v[26:33], v[216:223], v[46:49]
	v_mfma_f32_16x16x128_f8f6f4 v[42:45], v[18:25], v[216:223], v[42:45]
	s_setprio 0
	s_setprio 1
	v_mfma_f32_16x16x128_f8f6f4 v[86:89], v[10:17], v[192:199], v[86:89]
	v_mfma_f32_16x16x128_f8f6f4 v[82:85], v[2:9], v[192:199], v[82:85]
	v_mfma_f32_16x16x128_f8f6f4 v[70:73], v[10:17], v[200:207], v[70:73]
	v_mfma_f32_16x16x128_f8f6f4 v[66:69], v[2:9], v[200:207], v[66:69]
	v_mfma_f32_16x16x128_f8f6f4 v[54:57], v[10:17], v[208:215], v[54:57]
	v_mfma_f32_16x16x128_f8f6f4 v[50:53], v[2:9], v[208:215], v[50:53]
	v_mfma_f32_16x16x128_f8f6f4 v[38:41], v[10:17], v[216:223], v[38:41]
	v_mfma_f32_16x16x128_f8f6f4 v[34:37], v[2:9], v[216:223], v[34:37]
	s_setprio 0
	s_barrier
	s_add_i32 s58, 0, 0x18000
	s_add_i32 s59, 0, 0x1c000
	v_add_u32_e32 v14, s58, v186
	v_add_u32_e32 v30, s59, v186
	ds_read_b128 v[2:5], v14
	ds_read_b128 v[6:9], v14 offset:1024
	ds_read_b128 v[10:13], v14 offset:2048
	ds_read_b128 v[14:17], v14 offset:3072
	ds_read_b128 v[18:21], v30
	ds_read_b128 v[22:25], v30 offset:1024
	ds_read_b128 v[26:29], v30 offset:2048
	ds_read_b128 v[30:33], v30 offset:3072
	s_add_u32 s44, s44, 0x20000
	s_addc_u32 s45, s45, 0
	s_mov_b32 m0, s27
	v_lshl_add_u64 v[224:225], s[44:45], 0, v[168:169]
	ds_read_b128 v[192:195], v190 offset:32768
	ds_read_b128 v[196:199], v190 offset:33792
	ds_read_b128 v[200:203], v190 offset:34816
	ds_read_b128 v[204:207], v190 offset:35840
	ds_read_b128 v[208:211], v190 offset:36864
	ds_read_b128 v[212:215], v190 offset:37888
	ds_read_b128 v[216:219], v190 offset:38912
	ds_read_b128 v[220:223], v190 offset:39936
	global_load_lds_dwordx4 v[224:225], off
	v_lshl_add_u64 v[224:225], s[44:45], 0, v[164:165]
	s_mov_b32 m0, s33
	s_nop 0
	global_load_lds_dwordx4 v[224:225], off
	s_waitcnt vmcnt(8)
	s_waitcnt lgkmcnt(0)
	s_barrier
	s_setprio 1
	s_waitcnt lgkmcnt(0)
	v_mfma_f32_16x16x128_f8f6f4 v[158:161], v[2:9], v[192:199], v[158:161]
	v_mfma_f32_16x16x128_f8f6f4 v[154:157], v[10:17], v[192:199], v[154:157]
	v_mfma_f32_16x16x128_f8f6f4 v[142:145], v[2:9], v[200:207], v[142:145]
	v_mfma_f32_16x16x128_f8f6f4 v[138:141], v[10:17], v[200:207], v[138:141]
	v_mfma_f32_16x16x128_f8f6f4 v[126:129], v[2:9], v[208:215], v[126:129]
	v_mfma_f32_16x16x128_f8f6f4 v[122:125], v[10:17], v[208:215], v[122:125]
	v_mfma_f32_16x16x128_f8f6f4 v[110:113], v[2:9], v[216:223], v[110:113]
	v_mfma_f32_16x16x128_f8f6f4 v[106:109], v[10:17], v[216:223], v[106:109]
	s_setprio 0
	s_setprio 1
	v_mfma_f32_16x16x128_f8f6f4 v[150:153], v[18:25], v[192:199], v[150:153]
	v_mfma_f32_16x16x128_f8f6f4 v[146:149], v[26:33], v[192:199], v[146:149]
	v_mfma_f32_16x16x128_f8f6f4 v[134:137], v[18:25], v[200:207], v[134:137]
	v_mfma_f32_16x16x128_f8f6f4 v[130:133], v[26:33], v[200:207], v[130:133]
	v_mfma_f32_16x16x128_f8f6f4 v[118:121], v[18:25], v[208:215], v[118:121]
	v_mfma_f32_16x16x128_f8f6f4 v[114:117], v[26:33], v[208:215], v[114:117]
	v_mfma_f32_16x16x128_f8f6f4 v[102:105], v[18:25], v[216:223], v[102:105]
	v_mfma_f32_16x16x128_f8f6f4 v[98:101], v[26:33], v[216:223], v[98:101]
	s_setprio 0
	s_barrier
	s_add_i32 s44, s58, s2
	v_lshl_add_u64 v[178:179], v[178:179], 0, s[14:15]
	s_mov_b32 m0, s44
	ds_read_b128 v[192:195], v190 offset:49152
	ds_read_b128 v[196:199], v190 offset:50176
	ds_read_b128 v[200:203], v190 offset:51200
	ds_read_b128 v[204:207], v190 offset:52224
	ds_read_b128 v[208:211], v190 offset:53248
	ds_read_b128 v[212:215], v190 offset:54272
	ds_read_b128 v[216:219], v190 offset:55296
	ds_read_b128 v[220:223], v190 offset:56320
	global_load_lds_dwordx4 v[178:179], off
	s_add_i32 m0, s44, 0x2000
	s_add_u32 s0, s0, 0x20080
	v_lshl_add_u64 v[178:179], v[180:181], 0, s[14:15]
	s_addc_u32 s1, s1, 0
	s_add_i32 s44, s59, s2
	global_load_lds_dwordx4 v[178:179], off
	v_lshl_add_u64 v[178:179], s[0:1], 0, v[166:167]
	s_mov_b32 m0, s44
	s_nop 0
	global_load_lds_dwordx4 v[178:179], off
	v_lshl_add_u64 v[178:179], s[0:1], 0, v[162:163]
	s_add_i32 m0, s44, 0x2000
	s_nop 0
	global_load_lds_dwordx4 v[178:179], off
	v_lshl_add_u64 v[178:179], v[182:183], 0, s[14:15]
	s_mov_b32 m0, s35
	s_nop 0
	global_load_lds_dwordx4 v[178:179], off
	v_lshl_add_u64 v[178:179], v[184:185], 0, s[14:15]
	s_mov_b32 m0, s41
	s_nop 0
	global_load_lds_dwordx4 v[178:179], off
	s_waitcnt vmcnt(8)
	s_waitcnt lgkmcnt(0)
	s_barrier
	s_setprio 1
	s_waitcnt lgkmcnt(0)
	v_mfma_f32_16x16x128_f8f6f4 v[94:97], v[2:9], v[192:199], v[94:97]
	v_mfma_f32_16x16x128_f8f6f4 v[90:93], v[10:17], v[192:199], v[90:93]
	v_mfma_f32_16x16x128_f8f6f4 v[78:81], v[2:9], v[200:207], v[78:81]
	v_mfma_f32_16x16x128_f8f6f4 v[74:77], v[10:17], v[200:207], v[74:77]
	v_mfma_f32_16x16x128_f8f6f4 v[62:65], v[2:9], v[208:215], v[62:65]
	v_mfma_f32_16x16x128_f8f6f4 v[58:61], v[10:17], v[208:215], v[58:61]
	v_mfma_f32_16x16x128_f8f6f4 v[46:49], v[2:9], v[216:223], v[46:49]
	v_mfma_f32_16x16x128_f8f6f4 v[42:45], v[10:17], v[216:223], v[42:45]
	s_setprio 0
	s_setprio 1
	v_mfma_f32_16x16x128_f8f6f4 v[86:89], v[18:25], v[192:199], v[86:89]
	v_mfma_f32_16x16x128_f8f6f4 v[82:85], v[26:33], v[192:199], v[82:85]
	v_mfma_f32_16x16x128_f8f6f4 v[70:73], v[18:25], v[200:207], v[70:73]
	v_mfma_f32_16x16x128_f8f6f4 v[66:69], v[26:33], v[200:207], v[66:69]
	v_mfma_f32_16x16x128_f8f6f4 v[54:57], v[18:25], v[208:215], v[54:57]
	v_mfma_f32_16x16x128_f8f6f4 v[50:53], v[26:33], v[208:215], v[50:53]
	v_mfma_f32_16x16x128_f8f6f4 v[38:41], v[18:25], v[216:223], v[38:41]
	v_mfma_f32_16x16x128_f8f6f4 v[34:37], v[26:33], v[216:223], v[34:37]
	s_setprio 0
	s_add_i32 s57, s57, 2
	s_add_u32 s42, s42, 0x100
	s_addc_u32 s43, s43, 0
	s_add_u32 s55, s55, 0x100
	s_addc_u32 s56, s56, 0
	s_cmp_gt_u32 s57, 5
	s_barrier
	s_cbranch_scc0 .LBB0_892
	s_and_b64 vcc, exec, s[16:17]
	s_cbranch_vccz .LBB0_895
	s_barrier

.LBB0_967:
	ds_read_b128 v[26:29], v197
	ds_read_b128 v[30:33], v197 offset:1024
	ds_read_b128 v[18:21], v197 offset:2048
	ds_read_b128 v[22:25], v197 offset:3072
	ds_read_b128 v[10:13], v198
	ds_read_b128 v[14:17], v198 offset:1024
	ds_read_b128 v[2:5], v198 offset:2048
	ds_read_b128 v[6:9], v198 offset:3072
	s_add_u32 s0, s58, 0xfffc0080
	s_addc_u32 s1, s59, -1
	s_cmp_eq_u32 s77, 12
	s_cselect_b32 s61, s51, s1
	s_cselect_b32 s60, s57, s0
	s_cselect_b32 s1, s49, s76
	s_cselect_b32 s0, s74, s75
	v_lshl_add_u64 v[188:189], s[58:59], 0, v[172:173]
	s_add_i32 m0, s26, 0xc000
	ds_read_b128 v[180:183], v199
	ds_read_b128 v[184:187], v199 offset:1024
	ds_read_b128 v[202:205], v199 offset:2048
	ds_read_b128 v[206:209], v199 offset:3072
	ds_read_b128 v[210:213], v199 offset:4096
	ds_read_b128 v[214:217], v199 offset:5120
	ds_read_b128 v[218:221], v199 offset:6144
	ds_read_b128 v[222:225], v199 offset:7168
	global_load_lds_dwordx4 v[188:189], off
	v_lshl_add_u64 v[188:189], s[58:59], 0, v[174:175]
	s_add_i32 m0, s26, 0xe000
	s_nop 0
	global_load_lds_dwordx4 v[188:189], off
	s_waitcnt vmcnt(8)
	s_waitcnt lgkmcnt(0)
	s_barrier
	s_setprio 1
	s_waitcnt lgkmcnt(0)
	v_mfma_f32_16x16x128_f8f6f4 v[158:161], v[26:33], v[180:187], v[158:161]
	v_mfma_f32_16x16x128_f8f6f4 v[154:157], v[18:25], v[180:187], v[154:157]
	v_mfma_f32_16x16x128_f8f6f4 v[142:145], v[26:33], v[202:209], v[142:145]
	v_mfma_f32_16x16x128_f8f6f4 v[138:141], v[18:25], v[202:209], v[138:141]
	v_mfma_f32_16x16x128_f8f6f4 v[126:129], v[26:33], v[210:217], v[126:129]
	v_mfma_f32_16x16x128_f8f6f4 v[122:125], v[18:25], v[210:217], v[122:125]
	v_mfma_f32_16x16x128_f8f6f4 v[110:113], v[26:33], v[218:225], v[110:113]
	v_mfma_f32_16x16x128_f8f6f4 v[106:109], v[18:25], v[218:225], v[106:109]
	s_setprio 0
	s_setprio 1
	v_mfma_f32_16x16x128_f8f6f4 v[150:153], v[10:17], v[180:187], v[150:153]
	v_mfma_f32_16x16x128_f8f6f4 v[146:149], v[2:9], v[180:187], v[146:149]
	v_mfma_f32_16x16x128_f8f6f4 v[134:137], v[10:17], v[202:209], v[134:137]
	v_mfma_f32_16x16x128_f8f6f4 v[130:133], v[2:9], v[202:209], v[130:133]
	v_mfma_f32_16x16x128_f8f6f4 v[118:121], v[10:17], v[210:217], v[118:121]
	v_mfma_f32_16x16x128_f8f6f4 v[114:117], v[2:9], v[210:217], v[114:117]
	v_mfma_f32_16x16x128_f8f6f4 v[102:105], v[10:17], v[218:225], v[102:105]
	v_mfma_f32_16x16x128_f8f6f4 v[98:101], v[2:9], v[218:225], v[98:101]
	s_setprio 0
	s_barrier
	s_add_i32 s78, s70, s3
	v_lshl_add_u64 v[180:181], s[0:1], 0, v[164:165]
	s_mov_b32 m0, s78
	ds_read_b128 v[202:205], v199 offset:16384
	ds_read_b128 v[206:209], v199 offset:17408
	ds_read_b128 v[210:213], v199 offset:18432
	ds_read_b128 v[214:217], v199 offset:19456
	ds_read_b128 v[218:221], v199 offset:20480
	ds_read_b128 v[222:225], v199 offset:21504
	ds_read_b128 v[226:229], v199 offset:22528
	ds_read_b128 v[230:233], v199 offset:23552
	global_load_lds_dwordx4 v[180:181], off
	s_add_i32 m0, s78, 0x2000
	s_add_u32 s78, s0, 0x40000
	v_lshl_add_u64 v[182:183], s[0:1], 0, v[168:169]
	s_addc_u32 s79, s1, 0
	s_add_i32 s80, s71, s3
	global_load_lds_dwordx4 v[182:183], off
	v_lshl_add_u64 v[184:185], s[78:79], 0, v[164:165]
	s_mov_b32 m0, s80
	v_lshl_add_u64 v[186:187], s[60:61], 0, v[166:167]
	global_load_lds_dwordx4 v[184:185], off
	v_lshl_add_u64 v[184:185], s[78:79], 0, v[168:169]
	s_add_i32 m0, s80, 0x2000
	s_nop 0
	global_load_lds_dwordx4 v[184:185], off
	v_lshl_add_u64 v[184:185], s[60:61], 0, v[162:163]
	s_mov_b32 m0, s26
	s_nop 0
	global_load_lds_dwordx4 v[184:185], off
	s_mov_b32 m0, s27
	s_nop 0
	global_load_lds_dwordx4 v[186:187], off
	s_waitcnt vmcnt(8)
	s_waitcnt lgkmcnt(0)
	s_barrier
	s_setprio 1
	s_waitcnt lgkmcnt(0)
	v_mfma_f32_16x16x128_f8f6f4 v[94:97], v[26:33], v[202:209], v[94:97]
	v_mfma_f32_16x16x128_f8f6f4 v[90:93], v[18:25], v[202:209], v[90:93]
	v_mfma_f32_16x16x128_f8f6f4 v[78:81], v[26:33], v[210:217], v[78:81]
	v_mfma_f32_16x16x128_f8f6f4 v[74:77], v[18:25], v[210:217], v[74:77]
	v_mfma_f32_16x16x128_f8f6f4 v[62:65], v[26:33], v[218:225], v[62:65]
	v_mfma_f32_16x16x128_f8f6f4 v[58:61], v[18:25], v[218:225], v[58:61]
	v_mfma_f32_16x16x128_f8f6f4 v[46:49], v[26:33], v[226:233], v[46:49]
	v_mfma_f32_16x16x128_f8f6f4 v[42:45], v[18:25], v[226:233], v[42:45]
	s_setprio 0
	s_setprio 1
	v_mfma_f32_16x16x128_f8f6f4 v[86:89], v[10:17], v[202:209], v[86:89]
	v_mfma_f32_16x16x128_f8f6f4 v[82:85], v[2:9], v[202:209], v[82:85]
	v_mfma_f32_16x16x128_f8f6f4 v[70:73], v[10:17], v[210:217], v[70:73]
	v_mfma_f32_16x16x128_f8f6f4 v[66:69], v[2:9], v[210:217], v[66:69]
	v_mfma_f32_16x16x128_f8f6f4 v[54:57], v[10:17], v[218:225], v[54:57]
	v_mfma_f32_16x16x128_f8f6f4 v[50:53], v[2:9], v[218:225], v[50:53]
	v_mfma_f32_16x16x128_f8f6f4 v[38:41], v[10:17], v[226:233], v[38:41]
	v_mfma_f32_16x16x128_f8f6f4 v[34:37], v[2:9], v[226:233], v[34:37]
	s_setprio 0
	s_barrier
	s_add_i32 s78, 0, 0x18000
	s_add_i32 s79, 0, 0x1c000
	v_add_u32_e32 v14, s78, v195
	v_add_u32_e32 v30, s79, v195
	ds_read_b128 v[2:5], v14
	ds_read_b128 v[6:9], v14 offset:1024
	ds_read_b128 v[10:13], v14 offset:2048
	ds_read_b128 v[14:17], v14 offset:3072
	ds_read_b128 v[18:21], v30
	ds_read_b128 v[22:25], v30 offset:1024
	ds_read_b128 v[26:29], v30 offset:2048
	ds_read_b128 v[30:33], v30 offset:3072
	s_add_u32 s60, s60, 0x40000
	s_addc_u32 s61, s61, 0
	s_mov_b32 m0, s33
	v_lshl_add_u64 v[188:189], s[60:61], 0, v[162:163]
	ds_read_b128 v[202:205], v199 offset:32768
	ds_read_b128 v[206:209], v199 offset:33792
	ds_read_b128 v[210:213], v199 offset:34816
	ds_read_b128 v[214:217], v199 offset:35840
	ds_read_b128 v[218:221], v199 offset:36864
	ds_read_b128 v[222:225], v199 offset:37888
	ds_read_b128 v[226:229], v199 offset:38912
	ds_read_b128 v[230:233], v199 offset:39936
	global_load_lds_dwordx4 v[188:189], off
	v_lshl_add_u64 v[188:189], s[60:61], 0, v[166:167]
	s_mov_b32 m0, s34
	s_nop 0
	global_load_lds_dwordx4 v[188:189], off
	s_waitcnt vmcnt(8)
	s_waitcnt lgkmcnt(0)
	s_barrier
	s_setprio 1
	s_waitcnt lgkmcnt(0)
	v_mfma_f32_16x16x128_f8f6f4 v[158:161], v[2:9], v[202:209], v[158:161]
	v_mfma_f32_16x16x128_f8f6f4 v[154:157], v[10:17], v[202:209], v[154:157]
	v_mfma_f32_16x16x128_f8f6f4 v[142:145], v[2:9], v[210:217], v[142:145]
	v_mfma_f32_16x16x128_f8f6f4 v[138:141], v[10:17], v[210:217], v[138:141]
	v_mfma_f32_16x16x128_f8f6f4 v[126:129], v[2:9], v[218:225], v[126:129]
	v_mfma_f32_16x16x128_f8f6f4 v[122:125], v[10:17], v[218:225], v[122:125]
	v_mfma_f32_16x16x128_f8f6f4 v[110:113], v[2:9], v[226:233], v[110:113]
	v_mfma_f32_16x16x128_f8f6f4 v[106:109], v[10:17], v[226:233], v[106:109]
	s_setprio 0
	s_setprio 1
	v_mfma_f32_16x16x128_f8f6f4 v[150:153], v[18:25], v[202:209], v[150:153]
	v_mfma_f32_16x16x128_f8f6f4 v[146:149], v[26:33], v[202:209], v[146:149]
	v_mfma_f32_16x16x128_f8f6f4 v[134:137], v[18:25], v[210:217], v[134:137]
	v_mfma_f32_16x16x128_f8f6f4 v[130:133], v[26:33], v[210:217], v[130:133]
	v_mfma_f32_16x16x128_f8f6f4 v[118:121], v[18:25], v[218:225], v[118:121]
	v_mfma_f32_16x16x128_f8f6f4 v[114:117], v[26:33], v[218:225], v[114:117]
	v_mfma_f32_16x16x128_f8f6f4 v[102:105], v[18:25], v[226:233], v[102:105]
	v_mfma_f32_16x16x128_f8f6f4 v[98:101], v[26:33], v[226:233], v[98:101]
	s_setprio 0
	s_barrier
	s_add_i32 s60, s78, s3
	v_lshl_add_u64 v[180:181], v[180:181], 0, s[36:37]
	s_mov_b32 m0, s60
	ds_read_b128 v[202:205], v199 offset:49152
	ds_read_b128 v[206:209], v199 offset:50176
	ds_read_b128 v[210:213], v199 offset:51200
	ds_read_b128 v[214:217], v199 offset:52224
	ds_read_b128 v[218:221], v199 offset:53248
	ds_read_b128 v[222:225], v199 offset:54272
	ds_read_b128 v[226:229], v199 offset:55296
	ds_read_b128 v[230:233], v199 offset:56320
	global_load_lds_dwordx4 v[180:181], off
	s_add_i32 m0, s60, 0x2000
	s_add_u32 s0, s0, 0x40080
	v_lshl_add_u64 v[180:181], v[182:183], 0, s[36:37]
	s_addc_u32 s1, s1, 0
	s_add_i32 s60, s79, s3
	global_load_lds_dwordx4 v[180:181], off
	v_lshl_add_u64 v[180:181], s[0:1], 0, v[164:165]
	s_mov_b32 m0, s60
	s_nop 0
	global_load_lds_dwordx4 v[180:181], off
	v_lshl_add_u64 v[180:181], s[0:1], 0, v[168:169]
	s_add_i32 m0, s60, 0x2000
	s_nop 0
	global_load_lds_dwordx4 v[180:181], off
	v_lshl_add_u64 v[180:181], v[184:185], 0, s[36:37]
	s_mov_b32 m0, s64
	s_nop 0
	global_load_lds_dwordx4 v[180:181], off
	v_lshl_add_u64 v[180:181], v[186:187], 0, s[36:37]
	s_mov_b32 m0, s65
	s_nop 0
	global_load_lds_dwordx4 v[180:181], off
	s_waitcnt vmcnt(8)
	s_waitcnt lgkmcnt(0)
	s_barrier
	s_setprio 1
	s_waitcnt lgkmcnt(0)
	v_mfma_f32_16x16x128_f8f6f4 v[94:97], v[2:9], v[202:209], v[94:97]
	v_mfma_f32_16x16x128_f8f6f4 v[90:93], v[10:17], v[202:209], v[90:93]
	v_mfma_f32_16x16x128_f8f6f4 v[78:81], v[2:9], v[210:217], v[78:81]
	v_mfma_f32_16x16x128_f8f6f4 v[74:77], v[10:17], v[210:217], v[74:77]
	v_mfma_f32_16x16x128_f8f6f4 v[62:65], v[2:9], v[218:225], v[62:65]
	v_mfma_f32_16x16x128_f8f6f4 v[58:61], v[10:17], v[218:225], v[58:61]
	v_mfma_f32_16x16x128_f8f6f4 v[46:49], v[2:9], v[226:233], v[46:49]
	v_mfma_f32_16x16x128_f8f6f4 v[42:45], v[10:17], v[226:233], v[42:45]
	s_setprio 0
	s_setprio 1
	v_mfma_f32_16x16x128_f8f6f4 v[86:89], v[18:25], v[202:209], v[86:89]
	v_mfma_f32_16x16x128_f8f6f4 v[82:85], v[26:33], v[202:209], v[82:85]
	v_mfma_f32_16x16x128_f8f6f4 v[70:73], v[18:25], v[210:217], v[70:73]
	v_mfma_f32_16x16x128_f8f6f4 v[66:69], v[26:33], v[210:217], v[66:69]
	v_mfma_f32_16x16x128_f8f6f4 v[54:57], v[18:25], v[218:225], v[54:57]
	v_mfma_f32_16x16x128_f8f6f4 v[50:53], v[26:33], v[218:225], v[50:53]
	v_mfma_f32_16x16x128_f8f6f4 v[38:41], v[18:25], v[226:233], v[38:41]
	v_mfma_f32_16x16x128_f8f6f4 v[34:37], v[26:33], v[226:233], v[34:37]
	s_setprio 0
	s_add_i32 s77, s77, 2
	s_add_u32 s58, s58, 0x100
	s_addc_u32 s59, s59, 0
	s_add_u32 s75, s75, 0x100
	s_addc_u32 s76, s76, 0
	s_cmp_gt_u32 s77, 13
	s_barrier
	s_cbranch_scc0 .LBB0_967
	s_and_b64 vcc, exec, s[38:39]
	s_cbranch_vccz .LBB0_970
	s_barrier

.LBB0_1072:
	ds_read_b128 v[26:29], v190
	ds_read_b128 v[30:33], v190 offset:1024
	ds_read_b128 v[18:21], v190 offset:2048
	ds_read_b128 v[22:25], v190 offset:3072
	ds_read_b128 v[10:13], v191
	ds_read_b128 v[14:17], v191 offset:1024
	ds_read_b128 v[2:5], v191 offset:2048
	ds_read_b128 v[6:9], v191 offset:3072
	s_add_u32 s0, s36, 0xfffc0080
	s_addc_u32 s1, s37, -1
	s_cmp_eq_u32 s52, 12
	s_cselect_b32 s39, s23, s1
	s_cselect_b32 s38, s48, s0
	s_cselect_b32 s1, s19, s51
	s_cselect_b32 s0, s49, s50
	v_lshl_add_u64 v[220:221], s[36:37], 0, v[172:173]
	s_add_i32 m0, s25, 0xc000
	ds_read_b128 v[180:183], v192
	ds_read_b128 v[184:187], v192 offset:1024
	ds_read_b128 v[196:199], v192 offset:2048
	ds_read_b128 v[200:203], v192 offset:3072
	ds_read_b128 v[204:207], v192 offset:4096
	ds_read_b128 v[208:211], v192 offset:5120
	ds_read_b128 v[212:215], v192 offset:6144
	ds_read_b128 v[216:219], v192 offset:7168
	global_load_lds_dwordx4 v[220:221], off
	v_lshl_add_u64 v[220:221], s[36:37], 0, v[174:175]
	s_add_i32 m0, s25, 0xe000
	s_nop 0
	global_load_lds_dwordx4 v[220:221], off
	s_waitcnt vmcnt(8)
	s_waitcnt lgkmcnt(0)
	s_barrier
	s_setprio 1
	s_waitcnt lgkmcnt(0)
	v_mfma_f32_16x16x128_f8f6f4 v[158:161], v[26:33], v[180:187], v[158:161]
	v_mfma_f32_16x16x128_f8f6f4 v[154:157], v[18:25], v[180:187], v[154:157]
	v_mfma_f32_16x16x128_f8f6f4 v[142:145], v[26:33], v[196:203], v[142:145]
	v_mfma_f32_16x16x128_f8f6f4 v[138:141], v[18:25], v[196:203], v[138:141]
	v_mfma_f32_16x16x128_f8f6f4 v[126:129], v[26:33], v[204:211], v[126:129]
	v_mfma_f32_16x16x128_f8f6f4 v[122:125], v[18:25], v[204:211], v[122:125]
	v_mfma_f32_16x16x128_f8f6f4 v[110:113], v[26:33], v[212:219], v[110:113]
	v_mfma_f32_16x16x128_f8f6f4 v[106:109], v[18:25], v[212:219], v[106:109]
	s_setprio 0
	s_setprio 1
	v_mfma_f32_16x16x128_f8f6f4 v[150:153], v[10:17], v[180:187], v[150:153]
	v_mfma_f32_16x16x128_f8f6f4 v[146:149], v[2:9], v[180:187], v[146:149]
	v_mfma_f32_16x16x128_f8f6f4 v[134:137], v[10:17], v[196:203], v[134:137]
	v_mfma_f32_16x16x128_f8f6f4 v[130:133], v[2:9], v[196:203], v[130:133]
	v_mfma_f32_16x16x128_f8f6f4 v[118:121], v[10:17], v[204:211], v[118:121]
	v_mfma_f32_16x16x128_f8f6f4 v[114:117], v[2:9], v[204:211], v[114:117]
	v_mfma_f32_16x16x128_f8f6f4 v[102:105], v[10:17], v[212:219], v[102:105]
	v_mfma_f32_16x16x128_f8f6f4 v[98:101], v[2:9], v[212:219], v[98:101]
	s_setprio 0
	s_barrier
	s_add_i32 s53, s45, s21
	v_lshl_add_u64 v[180:181], s[0:1], 0, v[166:167]
	s_mov_b32 m0, s53
	ds_read_b128 v[196:199], v192 offset:16384
	ds_read_b128 v[200:203], v192 offset:17408
	ds_read_b128 v[204:207], v192 offset:18432
	ds_read_b128 v[208:211], v192 offset:19456
	ds_read_b128 v[212:215], v192 offset:20480
	ds_read_b128 v[216:219], v192 offset:21504
	ds_read_b128 v[220:223], v192 offset:22528
	ds_read_b128 v[224:227], v192 offset:23552
	global_load_lds_dwordx4 v[180:181], off
	s_add_i32 m0, s53, 0x2000
	s_add_u32 s54, s0, 0x40000
	v_lshl_add_u64 v[182:183], s[0:1], 0, v[162:163]
	s_addc_u32 s55, s1, 0
	s_add_i32 s53, s46, s21
	global_load_lds_dwordx4 v[182:183], off
	v_lshl_add_u64 v[184:185], s[54:55], 0, v[166:167]
	s_mov_b32 m0, s53
	v_lshl_add_u64 v[186:187], s[38:39], 0, v[164:165]
	global_load_lds_dwordx4 v[184:185], off
	v_lshl_add_u64 v[184:185], s[54:55], 0, v[162:163]
	s_add_i32 m0, s53, 0x2000
	s_nop 0
	global_load_lds_dwordx4 v[184:185], off
	v_lshl_add_u64 v[184:185], s[38:39], 0, v[168:169]
	s_mov_b32 m0, s25
	s_nop 0
	global_load_lds_dwordx4 v[184:185], off
	s_mov_b32 m0, s26
	s_nop 0
	global_load_lds_dwordx4 v[186:187], off
	s_waitcnt vmcnt(8)
	s_waitcnt lgkmcnt(0)
	s_barrier
	s_setprio 1
	s_waitcnt lgkmcnt(0)
	v_mfma_f32_16x16x128_f8f6f4 v[94:97], v[26:33], v[196:203], v[94:97]
	v_mfma_f32_16x16x128_f8f6f4 v[90:93], v[18:25], v[196:203], v[90:93]
	v_mfma_f32_16x16x128_f8f6f4 v[78:81], v[26:33], v[204:211], v[78:81]
	v_mfma_f32_16x16x128_f8f6f4 v[74:77], v[18:25], v[204:211], v[74:77]
	v_mfma_f32_16x16x128_f8f6f4 v[62:65], v[26:33], v[212:219], v[62:65]
	v_mfma_f32_16x16x128_f8f6f4 v[58:61], v[18:25], v[212:219], v[58:61]
	v_mfma_f32_16x16x128_f8f6f4 v[46:49], v[26:33], v[220:227], v[46:49]
	v_mfma_f32_16x16x128_f8f6f4 v[42:45], v[18:25], v[220:227], v[42:45]
	s_setprio 0
	s_setprio 1
	v_mfma_f32_16x16x128_f8f6f4 v[86:89], v[10:17], v[196:203], v[86:89]
	v_mfma_f32_16x16x128_f8f6f4 v[82:85], v[2:9], v[196:203], v[82:85]
	v_mfma_f32_16x16x128_f8f6f4 v[70:73], v[10:17], v[204:211], v[70:73]
	v_mfma_f32_16x16x128_f8f6f4 v[66:69], v[2:9], v[204:211], v[66:69]
	v_mfma_f32_16x16x128_f8f6f4 v[54:57], v[10:17], v[212:219], v[54:57]
	v_mfma_f32_16x16x128_f8f6f4 v[50:53], v[2:9], v[212:219], v[50:53]
	v_mfma_f32_16x16x128_f8f6f4 v[38:41], v[10:17], v[220:227], v[38:41]
	v_mfma_f32_16x16x128_f8f6f4 v[34:37], v[2:9], v[220:227], v[34:37]
	s_setprio 0
	s_barrier
	s_add_i32 s53, 0, 0x18000
	s_add_i32 s54, 0, 0x1c000
	v_add_u32_e32 v14, s53, v188
	v_add_u32_e32 v30, s54, v188
	ds_read_b128 v[2:5], v14
	ds_read_b128 v[6:9], v14 offset:1024
	ds_read_b128 v[10:13], v14 offset:2048
	ds_read_b128 v[14:17], v14 offset:3072
	ds_read_b128 v[18:21], v30
	ds_read_b128 v[22:25], v30 offset:1024
	ds_read_b128 v[26:29], v30 offset:2048
	ds_read_b128 v[30:33], v30 offset:3072
	s_add_u32 s38, s38, 0x40000
	s_addc_u32 s39, s39, 0
	s_mov_b32 m0, s27
	v_lshl_add_u64 v[228:229], s[38:39], 0, v[168:169]
	ds_read_b128 v[196:199], v192 offset:32768
	ds_read_b128 v[200:203], v192 offset:33792
	ds_read_b128 v[204:207], v192 offset:34816
	ds_read_b128 v[208:211], v192 offset:35840
	ds_read_b128 v[212:215], v192 offset:36864
	ds_read_b128 v[216:219], v192 offset:37888
	ds_read_b128 v[220:223], v192 offset:38912
	ds_read_b128 v[224:227], v192 offset:39936
	global_load_lds_dwordx4 v[228:229], off
	v_lshl_add_u64 v[228:229], s[38:39], 0, v[164:165]
	s_mov_b32 m0, s33
	s_nop 0
	global_load_lds_dwordx4 v[228:229], off
	s_waitcnt vmcnt(8)
	s_waitcnt lgkmcnt(0)
	s_barrier
	s_setprio 1
	s_waitcnt lgkmcnt(0)
	v_mfma_f32_16x16x128_f8f6f4 v[158:161], v[2:9], v[196:203], v[158:161]
	v_mfma_f32_16x16x128_f8f6f4 v[154:157], v[10:17], v[196:203], v[154:157]
	v_mfma_f32_16x16x128_f8f6f4 v[142:145], v[2:9], v[204:211], v[142:145]
	v_mfma_f32_16x16x128_f8f6f4 v[138:141], v[10:17], v[204:211], v[138:141]
	v_mfma_f32_16x16x128_f8f6f4 v[126:129], v[2:9], v[212:219], v[126:129]
	v_mfma_f32_16x16x128_f8f6f4 v[122:125], v[10:17], v[212:219], v[122:125]
	v_mfma_f32_16x16x128_f8f6f4 v[110:113], v[2:9], v[220:227], v[110:113]
	v_mfma_f32_16x16x128_f8f6f4 v[106:109], v[10:17], v[220:227], v[106:109]
	s_setprio 0
	s_setprio 1
	v_mfma_f32_16x16x128_f8f6f4 v[150:153], v[18:25], v[196:203], v[150:153]
	v_mfma_f32_16x16x128_f8f6f4 v[146:149], v[26:33], v[196:203], v[146:149]
	v_mfma_f32_16x16x128_f8f6f4 v[134:137], v[18:25], v[204:211], v[134:137]
	v_mfma_f32_16x16x128_f8f6f4 v[130:133], v[26:33], v[204:211], v[130:133]
	v_mfma_f32_16x16x128_f8f6f4 v[118:121], v[18:25], v[212:219], v[118:121]
	v_mfma_f32_16x16x128_f8f6f4 v[114:117], v[26:33], v[212:219], v[114:117]
	v_mfma_f32_16x16x128_f8f6f4 v[102:105], v[18:25], v[220:227], v[102:105]
	v_mfma_f32_16x16x128_f8f6f4 v[98:101], v[26:33], v[220:227], v[98:101]
	s_setprio 0
	s_barrier
	s_add_i32 s38, s53, s21
	v_lshl_add_u64 v[180:181], v[180:181], 0, s[12:13]
	s_mov_b32 m0, s38
	ds_read_b128 v[196:199], v192 offset:49152
	ds_read_b128 v[200:203], v192 offset:50176
	ds_read_b128 v[204:207], v192 offset:51200
	ds_read_b128 v[208:211], v192 offset:52224
	ds_read_b128 v[212:215], v192 offset:53248
	ds_read_b128 v[216:219], v192 offset:54272
	ds_read_b128 v[220:223], v192 offset:55296
	ds_read_b128 v[224:227], v192 offset:56320
	global_load_lds_dwordx4 v[180:181], off
	s_add_i32 m0, s38, 0x2000
	s_add_u32 s0, s0, 0x40080
	v_lshl_add_u64 v[180:181], v[182:183], 0, s[12:13]
	s_addc_u32 s1, s1, 0
	s_add_i32 s38, s54, s21
	global_load_lds_dwordx4 v[180:181], off
	v_lshl_add_u64 v[180:181], s[0:1], 0, v[166:167]
	s_mov_b32 m0, s38
	s_nop 0
	global_load_lds_dwordx4 v[180:181], off
	v_lshl_add_u64 v[180:181], s[0:1], 0, v[162:163]
	s_add_i32 m0, s38, 0x2000
	s_nop 0
	global_load_lds_dwordx4 v[180:181], off
	v_lshl_add_u64 v[180:181], v[184:185], 0, s[12:13]
	s_mov_b32 m0, s41
	s_nop 0
	global_load_lds_dwordx4 v[180:181], off
	v_lshl_add_u64 v[180:181], v[186:187], 0, s[12:13]
	s_mov_b32 m0, s42
	s_nop 0
	global_load_lds_dwordx4 v[180:181], off
	s_waitcnt vmcnt(8)
	s_waitcnt lgkmcnt(0)
	s_barrier
	s_setprio 1
	s_waitcnt lgkmcnt(0)
	v_mfma_f32_16x16x128_f8f6f4 v[94:97], v[2:9], v[196:203], v[94:97]
	v_mfma_f32_16x16x128_f8f6f4 v[90:93], v[10:17], v[196:203], v[90:93]
	v_mfma_f32_16x16x128_f8f6f4 v[78:81], v[2:9], v[204:211], v[78:81]
	v_mfma_f32_16x16x128_f8f6f4 v[74:77], v[10:17], v[204:211], v[74:77]
	v_mfma_f32_16x16x128_f8f6f4 v[62:65], v[2:9], v[212:219], v[62:65]
	v_mfma_f32_16x16x128_f8f6f4 v[58:61], v[10:17], v[212:219], v[58:61]
	v_mfma_f32_16x16x128_f8f6f4 v[46:49], v[2:9], v[220:227], v[46:49]
	v_mfma_f32_16x16x128_f8f6f4 v[42:45], v[10:17], v[220:227], v[42:45]
	s_setprio 0
	s_setprio 1
	v_mfma_f32_16x16x128_f8f6f4 v[86:89], v[18:25], v[196:203], v[86:89]
	v_mfma_f32_16x16x128_f8f6f4 v[82:85], v[26:33], v[196:203], v[82:85]
	v_mfma_f32_16x16x128_f8f6f4 v[70:73], v[18:25], v[204:211], v[70:73]
	v_mfma_f32_16x16x128_f8f6f4 v[66:69], v[26:33], v[204:211], v[66:69]
	v_mfma_f32_16x16x128_f8f6f4 v[54:57], v[18:25], v[212:219], v[54:57]
	v_mfma_f32_16x16x128_f8f6f4 v[50:53], v[26:33], v[212:219], v[50:53]
	v_mfma_f32_16x16x128_f8f6f4 v[38:41], v[18:25], v[220:227], v[38:41]
	v_mfma_f32_16x16x128_f8f6f4 v[34:37], v[26:33], v[220:227], v[34:37]
	s_setprio 0
	s_add_i32 s52, s52, 2
	s_add_u32 s36, s36, 0x100
	s_addc_u32 s37, s37, 0
	s_add_u32 s50, s50, 0x100
	s_addc_u32 s51, s51, 0
	s_cmp_gt_u32 s52, 13
	s_barrier
	s_cbranch_scc0 .LBB0_1072
	s_and_b64 vcc, exec, s[14:15]
	s_cbranch_vccz .LBB0_1075
	s_barrier

.LBB0_1159:
	ds_read_b128 v[26:29], v242
	ds_read_b128 v[30:33], v242 offset:1024
	ds_read_b128 v[18:21], v242 offset:2048
	ds_read_b128 v[22:25], v242 offset:3072
	ds_read_b128 v[10:13], v243
	ds_read_b128 v[14:17], v243 offset:1024
	ds_read_b128 v[2:5], v243 offset:2048
	ds_read_b128 v[6:9], v243 offset:3072
	s_add_i32 s20, s0, 2
	s_add_u32 s1, s10, 0xfff00080
	s_addc_u32 s12, s11, -1
	s_cmp_eq_u32 s15, s0
	s_cselect_b32 s0, s14, s18
	s_cselect_b32 s13, s5, s12
	s_cselect_b32 s12, s7, s1
	s_cselect_b32 s1, s9, s19
	v_lshl_add_u64 v[208:209], s[10:11], 0, v[194:195]
	s_add_i32 m0, s45, 0xc000
	ds_read_b128 v[162:165], v244
	ds_read_b128 v[166:169], v244 offset:1024
	ds_read_b128 v[170:173], v244 offset:2048
	ds_read_b128 v[174:177], v244 offset:3072
	ds_read_b128 v[178:181], v244 offset:4096
	ds_read_b128 v[182:185], v244 offset:5120
	ds_read_b128 v[200:203], v244 offset:6144
	ds_read_b128 v[204:207], v244 offset:7168
	global_load_lds_dwordx4 v[208:209], off
	v_lshl_add_u64 v[208:209], s[10:11], 0, v[196:197]
	s_add_i32 m0, s45, 0xe000
	s_nop 0
	global_load_lds_dwordx4 v[208:209], off
	s_waitcnt vmcnt(8)
	s_waitcnt lgkmcnt(0)
	s_barrier
	s_setprio 1
	s_waitcnt lgkmcnt(0)
	v_mfma_f32_16x16x128_f8f6f4 v[158:161], v[26:33], v[162:169], v[158:161]
	v_mfma_f32_16x16x128_f8f6f4 v[154:157], v[18:25], v[162:169], v[154:157]
	v_mfma_f32_16x16x128_f8f6f4 v[142:145], v[26:33], v[170:177], v[142:145]
	v_mfma_f32_16x16x128_f8f6f4 v[138:141], v[18:25], v[170:177], v[138:141]
	v_mfma_f32_16x16x128_f8f6f4 v[126:129], v[26:33], v[178:185], v[126:129]
	v_mfma_f32_16x16x128_f8f6f4 v[122:125], v[18:25], v[178:185], v[122:125]
	v_mfma_f32_16x16x128_f8f6f4 v[110:113], v[26:33], v[200:207], v[110:113]
	v_mfma_f32_16x16x128_f8f6f4 v[106:109], v[18:25], v[200:207], v[106:109]
	s_setprio 0
	s_setprio 1
	v_mfma_f32_16x16x128_f8f6f4 v[150:153], v[10:17], v[162:169], v[150:153]
	v_mfma_f32_16x16x128_f8f6f4 v[146:149], v[2:9], v[162:169], v[146:149]
	v_mfma_f32_16x16x128_f8f6f4 v[134:137], v[10:17], v[170:177], v[134:137]
	v_mfma_f32_16x16x128_f8f6f4 v[130:133], v[2:9], v[170:177], v[130:133]
	v_mfma_f32_16x16x128_f8f6f4 v[118:121], v[10:17], v[178:185], v[118:121]
	v_mfma_f32_16x16x128_f8f6f4 v[114:117], v[2:9], v[178:185], v[114:117]
	v_mfma_f32_16x16x128_f8f6f4 v[102:105], v[10:17], v[200:207], v[102:105]
	v_mfma_f32_16x16x128_f8f6f4 v[98:101], v[2:9], v[200:207], v[98:101]
	s_setprio 0
	s_barrier
	s_add_i32 s21, s84, s24
	v_lshl_add_u64 v[162:163], s[0:1], 0, v[188:189]
	s_mov_b32 m0, s21
	ds_read_b128 v[170:173], v244 offset:16384
	ds_read_b128 v[174:177], v244 offset:17408
	ds_read_b128 v[178:181], v244 offset:18432
	ds_read_b128 v[182:185], v244 offset:19456
	ds_read_b128 v[200:203], v244 offset:20480
	ds_read_b128 v[204:207], v244 offset:21504
	ds_read_b128 v[208:211], v244 offset:22528
	ds_read_b128 v[212:215], v244 offset:23552
	global_load_lds_dwordx4 v[162:163], off
	s_add_i32 m0, s21, 0x2000
	s_add_u32 s62, s0, 0x100000
	v_lshl_add_u64 v[164:165], s[0:1], 0, v[192:193]
	s_addc_u32 s63, s1, 0
	s_add_i32 s21, s85, s24
	global_load_lds_dwordx4 v[164:165], off
	v_lshl_add_u64 v[166:167], s[62:63], 0, v[188:189]
	s_mov_b32 m0, s21
	v_lshl_add_u64 v[168:169], s[12:13], 0, v[190:191]
	global_load_lds_dwordx4 v[166:167], off
	v_lshl_add_u64 v[166:167], s[62:63], 0, v[192:193]
	s_add_i32 m0, s21, 0x2000
	s_nop 0
	global_load_lds_dwordx4 v[166:167], off
	v_lshl_add_u64 v[166:167], s[12:13], 0, v[186:187]
	s_mov_b32 m0, s45
	s_nop 0
	global_load_lds_dwordx4 v[166:167], off
	s_mov_b32 m0, s68
	s_nop 0
	global_load_lds_dwordx4 v[168:169], off
	s_waitcnt vmcnt(8)
	s_waitcnt lgkmcnt(0)
	s_barrier
	s_setprio 1
	s_waitcnt lgkmcnt(0)
	v_mfma_f32_16x16x128_f8f6f4 v[94:97], v[26:33], v[170:177], v[94:97]
	v_mfma_f32_16x16x128_f8f6f4 v[90:93], v[18:25], v[170:177], v[90:93]
	v_mfma_f32_16x16x128_f8f6f4 v[78:81], v[26:33], v[178:185], v[78:81]
	v_mfma_f32_16x16x128_f8f6f4 v[74:77], v[18:25], v[178:185], v[74:77]
	v_mfma_f32_16x16x128_f8f6f4 v[62:65], v[26:33], v[200:207], v[62:65]
	v_mfma_f32_16x16x128_f8f6f4 v[58:61], v[18:25], v[200:207], v[58:61]
	v_mfma_f32_16x16x128_f8f6f4 v[46:49], v[26:33], v[208:215], v[46:49]
	v_mfma_f32_16x16x128_f8f6f4 v[42:45], v[18:25], v[208:215], v[42:45]
	s_setprio 0
	s_setprio 1
	v_mfma_f32_16x16x128_f8f6f4 v[86:89], v[10:17], v[170:177], v[86:89]
	v_mfma_f32_16x16x128_f8f6f4 v[82:85], v[2:9], v[170:177], v[82:85]
	v_mfma_f32_16x16x128_f8f6f4 v[70:73], v[10:17], v[178:185], v[70:73]
	v_mfma_f32_16x16x128_f8f6f4 v[66:69], v[2:9], v[178:185], v[66:69]
	v_mfma_f32_16x16x128_f8f6f4 v[54:57], v[10:17], v[200:207], v[54:57]
	v_mfma_f32_16x16x128_f8f6f4 v[50:53], v[2:9], v[200:207], v[50:53]
	v_mfma_f32_16x16x128_f8f6f4 v[38:41], v[10:17], v[208:215], v[38:41]
	v_mfma_f32_16x16x128_f8f6f4 v[34:37], v[2:9], v[208:215], v[34:37]
	s_setprio 0
	s_barrier
	s_add_i32 s21, 0, 0x18000
	s_add_i32 s51, 0, 0x1c000
	v_add_u32_e32 v14, s21, v240
	v_add_u32_e32 v30, s51, v240
	ds_read_b128 v[2:5], v14
	ds_read_b128 v[6:9], v14 offset:1024
	ds_read_b128 v[10:13], v14 offset:2048
	ds_read_b128 v[14:17], v14 offset:3072
	ds_read_b128 v[18:21], v30
	ds_read_b128 v[22:25], v30 offset:1024
	ds_read_b128 v[26:29], v30 offset:2048
	ds_read_b128 v[30:33], v30 offset:3072
	s_add_u32 s12, s12, 0x100000
	s_addc_u32 s13, s13, 0
	s_mov_b32 m0, s69
	v_lshl_add_u64 v[216:217], s[12:13], 0, v[186:187]
	ds_read_b128 v[170:173], v244 offset:32768
	ds_read_b128 v[174:177], v244 offset:33792
	ds_read_b128 v[178:181], v244 offset:34816
	ds_read_b128 v[182:185], v244 offset:35840
	ds_read_b128 v[200:203], v244 offset:36864
	ds_read_b128 v[204:207], v244 offset:37888
	ds_read_b128 v[208:211], v244 offset:38912
	ds_read_b128 v[212:215], v244 offset:39936
	global_load_lds_dwordx4 v[216:217], off
	v_lshl_add_u64 v[216:217], s[12:13], 0, v[190:191]
	s_mov_b32 m0, s70
	s_nop 0
	global_load_lds_dwordx4 v[216:217], off
	s_waitcnt vmcnt(8)
	s_waitcnt lgkmcnt(0)
	s_barrier
	s_setprio 1
	s_waitcnt lgkmcnt(0)
	v_mfma_f32_16x16x128_f8f6f4 v[158:161], v[2:9], v[170:177], v[158:161]
	v_mfma_f32_16x16x128_f8f6f4 v[154:157], v[10:17], v[170:177], v[154:157]
	v_mfma_f32_16x16x128_f8f6f4 v[142:145], v[2:9], v[178:185], v[142:145]
	v_mfma_f32_16x16x128_f8f6f4 v[138:141], v[10:17], v[178:185], v[138:141]
	v_mfma_f32_16x16x128_f8f6f4 v[126:129], v[2:9], v[200:207], v[126:129]
	v_mfma_f32_16x16x128_f8f6f4 v[122:125], v[10:17], v[200:207], v[122:125]
	v_mfma_f32_16x16x128_f8f6f4 v[110:113], v[2:9], v[208:215], v[110:113]
	v_mfma_f32_16x16x128_f8f6f4 v[106:109], v[10:17], v[208:215], v[106:109]
	s_setprio 0
	s_setprio 1
	v_mfma_f32_16x16x128_f8f6f4 v[150:153], v[18:25], v[170:177], v[150:153]
	v_mfma_f32_16x16x128_f8f6f4 v[146:149], v[26:33], v[170:177], v[146:149]
	v_mfma_f32_16x16x128_f8f6f4 v[134:137], v[18:25], v[178:185], v[134:137]
	v_mfma_f32_16x16x128_f8f6f4 v[130:133], v[26:33], v[178:185], v[130:133]
	v_mfma_f32_16x16x128_f8f6f4 v[118:121], v[18:25], v[200:207], v[118:121]
	v_mfma_f32_16x16x128_f8f6f4 v[114:117], v[26:33], v[200:207], v[114:117]
	v_mfma_f32_16x16x128_f8f6f4 v[102:105], v[18:25], v[208:215], v[102:105]
	v_mfma_f32_16x16x128_f8f6f4 v[98:101], v[26:33], v[208:215], v[98:101]
	s_setprio 0
	s_barrier
	s_add_i32 s12, s21, s24
	v_lshl_add_u64 v[162:163], v[162:163], 0, s[36:37]
	s_mov_b32 m0, s12
	ds_read_b128 v[170:173], v244 offset:49152
	ds_read_b128 v[174:177], v244 offset:50176
	ds_read_b128 v[178:181], v244 offset:51200
	ds_read_b128 v[182:185], v244 offset:52224
	ds_read_b128 v[200:203], v244 offset:53248
	ds_read_b128 v[204:207], v244 offset:54272
	ds_read_b128 v[208:211], v244 offset:55296
	ds_read_b128 v[212:215], v244 offset:56320
	global_load_lds_dwordx4 v[162:163], off
	s_add_i32 m0, s12, 0x2000
	s_add_u32 s0, s0, 0x100080
	v_lshl_add_u64 v[162:163], v[164:165], 0, s[36:37]
	s_addc_u32 s1, s1, 0
	s_add_i32 s12, s51, s24
	global_load_lds_dwordx4 v[162:163], off
	v_lshl_add_u64 v[162:163], s[0:1], 0, v[188:189]
	s_mov_b32 m0, s12
	s_nop 0
	global_load_lds_dwordx4 v[162:163], off
	v_lshl_add_u64 v[162:163], s[0:1], 0, v[192:193]
	s_add_i32 m0, s12, 0x2000
	s_nop 0
	global_load_lds_dwordx4 v[162:163], off
	v_lshl_add_u64 v[162:163], v[166:167], 0, s[36:37]
	s_mov_b32 m0, s77
	s_nop 0
	global_load_lds_dwordx4 v[162:163], off
	v_lshl_add_u64 v[162:163], v[168:169], 0, s[36:37]
	s_mov_b32 m0, s78
	s_nop 0
	global_load_lds_dwordx4 v[162:163], off
	s_waitcnt vmcnt(8)
	s_waitcnt lgkmcnt(0)
	s_barrier
	s_setprio 1
	s_waitcnt lgkmcnt(0)
	v_mfma_f32_16x16x128_f8f6f4 v[94:97], v[2:9], v[170:177], v[94:97]
	v_mfma_f32_16x16x128_f8f6f4 v[90:93], v[10:17], v[170:177], v[90:93]
	v_mfma_f32_16x16x128_f8f6f4 v[78:81], v[2:9], v[178:185], v[78:81]
	v_mfma_f32_16x16x128_f8f6f4 v[74:77], v[10:17], v[178:185], v[74:77]
	v_mfma_f32_16x16x128_f8f6f4 v[62:65], v[2:9], v[200:207], v[62:65]
	v_mfma_f32_16x16x128_f8f6f4 v[58:61], v[10:17], v[200:207], v[58:61]
	v_mfma_f32_16x16x128_f8f6f4 v[46:49], v[2:9], v[208:215], v[46:49]
	v_mfma_f32_16x16x128_f8f6f4 v[42:45], v[10:17], v[208:215], v[42:45]
	s_setprio 0
	s_setprio 1
	v_mfma_f32_16x16x128_f8f6f4 v[86:89], v[18:25], v[170:177], v[86:89]
	v_mfma_f32_16x16x128_f8f6f4 v[82:85], v[26:33], v[170:177], v[82:85]
	v_mfma_f32_16x16x128_f8f6f4 v[70:73], v[18:25], v[178:185], v[70:73]
	v_mfma_f32_16x16x128_f8f6f4 v[66:69], v[26:33], v[178:185], v[66:69]
	v_mfma_f32_16x16x128_f8f6f4 v[54:57], v[18:25], v[200:207], v[54:57]
	v_mfma_f32_16x16x128_f8f6f4 v[50:53], v[26:33], v[200:207], v[50:53]
	v_mfma_f32_16x16x128_f8f6f4 v[38:41], v[18:25], v[208:215], v[38:41]
	v_mfma_f32_16x16x128_f8f6f4 v[34:37], v[26:33], v[208:215], v[34:37]
	s_setprio 0
	s_add_u32 s10, s10, 0x100
	s_addc_u32 s11, s11, 0
	s_add_u32 s18, s18, 0x100
	s_addc_u32 s19, s19, 0
	s_cmp_ge_i32 s20, s17
	s_mov_b32 s0, s20
	s_barrier
	s_cbranch_scc0 .LBB0_1159
	s_and_b64 vcc, exec, s[38:39]
	s_cbranch_vccz .LBB0_1162
